# K-loop LDS-DMA loads use SGPR-base (saddr) addressing: no 64-bit VALU address adds in the load segments
# speedup vs baseline: 1.0730x; 1.0061x over previous
.LBB0_48:
	s_add_i32 s52, s8, 2
	s_add_u32 s9, s4, 0xfffc0080
	s_addc_u32 s53, s5, -1
	s_add_i32 s54, 0, 0x10000
	s_cmp_eq_u32 s33, s8
	s_cselect_b32 vcc_hi, s15, s53
	s_cselect_b32 vcc_lo, s14, s9
	s_cselect_b32 s9, s35, s69
	s_cselect_b32 s8, s34, s68
	s_add_i32 s53, 0, 0x14000
	v_add_u32_e32 v140, s54, v188
	v_add_u32_e32 v156, s53, v188
	ds_read_b128 v[128:131], v140
	ds_read_b128 v[132:135], v140 offset:1024
	ds_read_b128 v[136:139], v140 offset:2048
	ds_read_b128 v[140:143], v140 offset:3072
	ds_read_b128 v[144:147], v156
	ds_read_b128 v[148:151], v156 offset:1024
	ds_read_b128 v[152:155], v156 offset:2048
	ds_read_b128 v[156:159], v156 offset:3072
	s_add_i32 m0, s10, 0xc000
	ds_read_b128 v[172:175], v189
	ds_read_b128 v[176:179], v189 offset:1024
	ds_read_b128 v[180:183], v189 offset:2048
	ds_read_b128 v[184:187], v189 offset:3072
	ds_read_b128 v[212:215], v189 offset:4096
	ds_read_b128 v[216:219], v189 offset:5120
	ds_read_b128 v[220:223], v189 offset:6144
	ds_read_b128 v[224:227], v189 offset:7168
	global_load_lds_dwordx4 v170, s[4:5]
	s_add_i32 m0, s10, 0xe000
	s_nop 0
	global_load_lds_dwordx4 v168, s[4:5]
	s_waitcnt vmcnt(8)
	s_waitcnt lgkmcnt(0)
	s_barrier
	s_setprio 1
	s_waitcnt lgkmcnt(0)
	v_mfma_f32_16x16x32_bf16 v[124:127], v[128:131], v[172:175], v[124:127]
	v_mfma_f32_16x16x32_bf16 v[60:63], v[136:139], v[172:175], v[60:63]
	v_mfma_f32_16x16x32_bf16 v[116:119], v[128:131], v[180:183], v[116:119]
	v_mfma_f32_16x16x32_bf16 v[52:55], v[136:139], v[180:183], v[52:55]
	v_mfma_f32_16x16x32_bf16 v[108:111], v[128:131], v[212:215], v[108:111]
	v_mfma_f32_16x16x32_bf16 v[44:47], v[136:139], v[212:215], v[44:47]
	v_mfma_f32_16x16x32_bf16 v[100:103], v[128:131], v[220:223], v[100:103]
	v_mfma_f32_16x16x32_bf16 v[36:39], v[136:139], v[220:223], v[36:39]
	v_mfma_f32_16x16x32_bf16 v[124:127], v[132:135], v[176:179], v[124:127]
	v_mfma_f32_16x16x32_bf16 v[60:63], v[140:143], v[176:179], v[60:63]
	v_mfma_f32_16x16x32_bf16 v[116:119], v[132:135], v[184:187], v[116:119]
	v_mfma_f32_16x16x32_bf16 v[52:55], v[140:143], v[184:187], v[52:55]
	v_mfma_f32_16x16x32_bf16 v[108:111], v[132:135], v[216:219], v[108:111]
	v_mfma_f32_16x16x32_bf16 v[44:47], v[140:143], v[216:219], v[44:47]
	v_mfma_f32_16x16x32_bf16 v[100:103], v[132:135], v[224:227], v[100:103]
	v_mfma_f32_16x16x32_bf16 v[36:39], v[140:143], v[224:227], v[36:39]
	s_setprio 0
	s_setprio 1
	v_mfma_f32_16x16x32_bf16 v[120:123], v[144:147], v[172:175], v[120:123]
	v_mfma_f32_16x16x32_bf16 v[56:59], v[152:155], v[172:175], v[56:59]
	v_mfma_f32_16x16x32_bf16 v[112:115], v[144:147], v[180:183], v[112:115]
	v_mfma_f32_16x16x32_bf16 v[48:51], v[152:155], v[180:183], v[48:51]
	v_mfma_f32_16x16x32_bf16 v[104:107], v[144:147], v[212:215], v[104:107]
	v_mfma_f32_16x16x32_bf16 v[40:43], v[152:155], v[212:215], v[40:43]
	v_mfma_f32_16x16x32_bf16 v[96:99], v[144:147], v[220:223], v[96:99]
	v_mfma_f32_16x16x32_bf16 v[32:35], v[152:155], v[220:223], v[32:35]
	v_mfma_f32_16x16x32_bf16 v[120:123], v[148:151], v[176:179], v[120:123]
	v_mfma_f32_16x16x32_bf16 v[56:59], v[156:159], v[176:179], v[56:59]
	v_mfma_f32_16x16x32_bf16 v[112:115], v[148:151], v[184:187], v[112:115]
	v_mfma_f32_16x16x32_bf16 v[48:51], v[156:159], v[184:187], v[48:51]
	v_mfma_f32_16x16x32_bf16 v[104:107], v[148:151], v[216:219], v[104:107]
	v_mfma_f32_16x16x32_bf16 v[40:43], v[156:159], v[216:219], v[40:43]
	v_mfma_f32_16x16x32_bf16 v[96:99], v[148:151], v[224:227], v[96:99]
	v_mfma_f32_16x16x32_bf16 v[32:35], v[156:159], v[224:227], v[32:35]
	s_setprio 0
	s_barrier
	s_add_i32 s54, s54, s13
	s_mov_b32 m0, s54
	ds_read_b128 v[172:175], v189 offset:16384
	ds_read_b128 v[176:179], v189 offset:17408
	ds_read_b128 v[180:183], v189 offset:18432
	ds_read_b128 v[184:187], v189 offset:19456
	ds_read_b128 v[212:215], v189 offset:20480
	ds_read_b128 v[216:219], v189 offset:21504
	ds_read_b128 v[220:223], v189 offset:22528
	ds_read_b128 v[224:227], v189 offset:23552
	global_load_lds_dwordx4 v164, s[8:9]
	s_add_i32 m0, s54, 0x2000
	s_add_u32 s54, s8, 0x40000
	s_addc_u32 s55, s9, 0
	s_add_i32 s53, s53, s13
	global_load_lds_dwordx4 v160, s[8:9]
	s_mov_b32 m0, s53
	s_nop 0
	global_load_lds_dwordx4 v164, s[54:55]
	s_add_i32 m0, s53, 0x2000
	s_nop 0
	global_load_lds_dwordx4 v160, s[54:55]
	s_mov_b32 m0, s10
	s_nop 0
	global_load_lds_dwordx4 v166, vcc
	s_mov_b32 m0, s11
	s_nop 0
	global_load_lds_dwordx4 v162, vcc
	s_waitcnt vmcnt(8)
	s_waitcnt lgkmcnt(0)
	s_barrier
	s_setprio 1
	s_waitcnt lgkmcnt(0)
	v_mfma_f32_16x16x32_bf16 v[92:95], v[128:131], v[172:175], v[92:95]
	v_mfma_f32_16x16x32_bf16 v[28:31], v[136:139], v[172:175], v[28:31]
	v_mfma_f32_16x16x32_bf16 v[84:87], v[128:131], v[180:183], v[84:87]
	v_mfma_f32_16x16x32_bf16 v[20:23], v[136:139], v[180:183], v[20:23]
	v_mfma_f32_16x16x32_bf16 v[76:79], v[128:131], v[212:215], v[76:79]
	v_mfma_f32_16x16x32_bf16 v[12:15], v[136:139], v[212:215], v[12:15]
	v_mfma_f32_16x16x32_bf16 v[72:75], v[128:131], v[220:223], v[72:75]
	v_mfma_f32_16x16x32_bf16 v[4:7], v[136:139], v[220:223], v[4:7]
	v_mfma_f32_16x16x32_bf16 v[92:95], v[132:135], v[176:179], v[92:95]
	v_mfma_f32_16x16x32_bf16 v[28:31], v[140:143], v[176:179], v[28:31]
	v_mfma_f32_16x16x32_bf16 v[84:87], v[132:135], v[184:187], v[84:87]
	v_mfma_f32_16x16x32_bf16 v[20:23], v[140:143], v[184:187], v[20:23]
	v_mfma_f32_16x16x32_bf16 v[76:79], v[132:135], v[216:219], v[76:79]
	v_mfma_f32_16x16x32_bf16 v[12:15], v[140:143], v[216:219], v[12:15]
	v_mfma_f32_16x16x32_bf16 v[72:75], v[132:135], v[224:227], v[72:75]
	v_mfma_f32_16x16x32_bf16 v[4:7], v[140:143], v[224:227], v[4:7]
	s_setprio 0
	s_setprio 1
	v_mfma_f32_16x16x32_bf16 v[88:91], v[144:147], v[172:175], v[88:91]
	v_mfma_f32_16x16x32_bf16 v[24:27], v[152:155], v[172:175], v[24:27]
	v_mfma_f32_16x16x32_bf16 v[80:83], v[144:147], v[180:183], v[80:83]
	v_mfma_f32_16x16x32_bf16 v[16:19], v[152:155], v[180:183], v[16:19]
	v_mfma_f32_16x16x32_bf16 v[68:71], v[144:147], v[212:215], v[68:71]
	v_mfma_f32_16x16x32_bf16 v[8:11], v[152:155], v[212:215], v[8:11]
	v_mfma_f32_16x16x32_bf16 v[64:67], v[144:147], v[220:223], v[64:67]
	v_mfma_f32_16x16x32_bf16 v[0:3], v[152:155], v[220:223], v[0:3]
	v_mfma_f32_16x16x32_bf16 v[88:91], v[148:151], v[176:179], v[88:91]
	v_mfma_f32_16x16x32_bf16 v[24:27], v[156:159], v[176:179], v[24:27]
	v_mfma_f32_16x16x32_bf16 v[80:83], v[148:151], v[184:187], v[80:83]
	v_mfma_f32_16x16x32_bf16 v[16:19], v[156:159], v[184:187], v[16:19]
	v_mfma_f32_16x16x32_bf16 v[68:71], v[148:151], v[216:219], v[68:71]
	v_mfma_f32_16x16x32_bf16 v[8:11], v[156:159], v[216:219], v[8:11]
	v_mfma_f32_16x16x32_bf16 v[64:67], v[148:151], v[224:227], v[64:67]
	v_mfma_f32_16x16x32_bf16 v[0:3], v[156:159], v[224:227], v[0:3]
	s_setprio 0
	s_barrier
	s_add_i32 s53, 0, 0x18000
	s_add_i32 s56, 0, 0x1c000
	v_add_u32_e32 v140, s53, v188
	v_add_u32_e32 v156, s56, v188
	ds_read_b128 v[128:131], v140
	ds_read_b128 v[132:135], v140 offset:1024
	ds_read_b128 v[136:139], v140 offset:2048
	ds_read_b128 v[140:143], v140 offset:3072
	ds_read_b128 v[144:147], v156
	ds_read_b128 v[148:151], v156 offset:1024
	ds_read_b128 v[152:155], v156 offset:2048
	ds_read_b128 v[156:159], v156 offset:3072
	s_add_u32 s54, vcc_lo, 0x40000
	s_addc_u32 s55, vcc_hi, 0
	s_mov_b32 m0, s72
	s_nop 0
	ds_read_b128 v[172:175], v189 offset:32768
	ds_read_b128 v[176:179], v189 offset:33792
	ds_read_b128 v[180:183], v189 offset:34816
	ds_read_b128 v[184:187], v189 offset:35840
	ds_read_b128 v[212:215], v189 offset:36864
	ds_read_b128 v[216:219], v189 offset:37888
	ds_read_b128 v[220:223], v189 offset:38912
	ds_read_b128 v[224:227], v189 offset:39936
	global_load_lds_dwordx4 v166, s[54:55]
	s_mov_b32 m0, s73
	s_nop 0
	global_load_lds_dwordx4 v162, s[54:55]
	s_waitcnt vmcnt(8)
	s_waitcnt lgkmcnt(0)
	s_barrier
	s_setprio 1
	s_waitcnt lgkmcnt(0)
	v_mfma_f32_16x16x32_bf16 v[124:127], v[128:131], v[172:175], v[124:127]
	v_mfma_f32_16x16x32_bf16 v[60:63], v[136:139], v[172:175], v[60:63]
	v_mfma_f32_16x16x32_bf16 v[116:119], v[128:131], v[180:183], v[116:119]
	v_mfma_f32_16x16x32_bf16 v[52:55], v[136:139], v[180:183], v[52:55]
	v_mfma_f32_16x16x32_bf16 v[108:111], v[128:131], v[212:215], v[108:111]
	v_mfma_f32_16x16x32_bf16 v[44:47], v[136:139], v[212:215], v[44:47]
	v_mfma_f32_16x16x32_bf16 v[100:103], v[128:131], v[220:223], v[100:103]
	v_mfma_f32_16x16x32_bf16 v[36:39], v[136:139], v[220:223], v[36:39]
	v_mfma_f32_16x16x32_bf16 v[124:127], v[132:135], v[176:179], v[124:127]
	v_mfma_f32_16x16x32_bf16 v[60:63], v[140:143], v[176:179], v[60:63]
	v_mfma_f32_16x16x32_bf16 v[116:119], v[132:135], v[184:187], v[116:119]
	v_mfma_f32_16x16x32_bf16 v[52:55], v[140:143], v[184:187], v[52:55]
	v_mfma_f32_16x16x32_bf16 v[108:111], v[132:135], v[216:219], v[108:111]
	v_mfma_f32_16x16x32_bf16 v[44:47], v[140:143], v[216:219], v[44:47]
	v_mfma_f32_16x16x32_bf16 v[100:103], v[132:135], v[224:227], v[100:103]
	v_mfma_f32_16x16x32_bf16 v[36:39], v[140:143], v[224:227], v[36:39]
	s_setprio 0
	s_setprio 1
	v_mfma_f32_16x16x32_bf16 v[120:123], v[144:147], v[172:175], v[120:123]
	v_mfma_f32_16x16x32_bf16 v[56:59], v[152:155], v[172:175], v[56:59]
	v_mfma_f32_16x16x32_bf16 v[112:115], v[144:147], v[180:183], v[112:115]
	v_mfma_f32_16x16x32_bf16 v[48:51], v[152:155], v[180:183], v[48:51]
	v_mfma_f32_16x16x32_bf16 v[104:107], v[144:147], v[212:215], v[104:107]
	v_mfma_f32_16x16x32_bf16 v[40:43], v[152:155], v[212:215], v[40:43]
	v_mfma_f32_16x16x32_bf16 v[96:99], v[144:147], v[220:223], v[96:99]
	v_mfma_f32_16x16x32_bf16 v[32:35], v[152:155], v[220:223], v[32:35]
	v_mfma_f32_16x16x32_bf16 v[120:123], v[148:151], v[176:179], v[120:123]
	v_mfma_f32_16x16x32_bf16 v[56:59], v[156:159], v[176:179], v[56:59]
	v_mfma_f32_16x16x32_bf16 v[112:115], v[148:151], v[184:187], v[112:115]
	v_mfma_f32_16x16x32_bf16 v[48:51], v[156:159], v[184:187], v[48:51]
	v_mfma_f32_16x16x32_bf16 v[104:107], v[148:151], v[216:219], v[104:107]
	v_mfma_f32_16x16x32_bf16 v[40:43], v[156:159], v[216:219], v[40:43]
	v_mfma_f32_16x16x32_bf16 v[96:99], v[148:151], v[224:227], v[96:99]
	v_mfma_f32_16x16x32_bf16 v[32:35], v[156:159], v[224:227], v[32:35]
	s_setprio 0
	s_barrier
	s_add_i32 s53, s53, s13
	s_add_i32 m0, s53, 0xffffff80
	ds_read_b128 v[172:175], v189 offset:49152
	ds_read_b128 v[176:179], v189 offset:50176
	ds_read_b128 v[180:183], v189 offset:51200
	ds_read_b128 v[184:187], v189 offset:52224
	ds_read_b128 v[212:215], v189 offset:53248
	ds_read_b128 v[216:219], v189 offset:54272
	ds_read_b128 v[220:223], v189 offset:55296
	ds_read_b128 v[224:227], v189 offset:56320
	global_load_lds_dwordx4 v164, s[8:9] offset:128
	s_add_i32 m0, s53, 0x1f80
	s_nop 0
	s_add_i32 s53, s56, s13
	global_load_lds_dwordx4 v160, s[8:9] offset:128
	s_add_u32 s8, s8, 0x40080
	s_addc_u32 s9, s9, 0
	s_mov_b32 m0, s53
	s_nop 0
	global_load_lds_dwordx4 v164, s[8:9]
	s_add_i32 m0, s53, 0x2000
	s_nop 0
	global_load_lds_dwordx4 v160, s[8:9]
	s_add_i32 m0, s12, 0xffffff80
	s_nop 0
	global_load_lds_dwordx4 v166, vcc offset:128
	s_add_i32 m0, s50, 0xffffff80
	s_nop 0
	global_load_lds_dwordx4 v162, vcc offset:128
	s_waitcnt vmcnt(8)
	s_waitcnt lgkmcnt(0)
	s_barrier
	s_setprio 1
	s_waitcnt lgkmcnt(0)
	v_mfma_f32_16x16x32_bf16 v[92:95], v[128:131], v[172:175], v[92:95]
	v_mfma_f32_16x16x32_bf16 v[28:31], v[136:139], v[172:175], v[28:31]
	v_mfma_f32_16x16x32_bf16 v[84:87], v[128:131], v[180:183], v[84:87]
	v_mfma_f32_16x16x32_bf16 v[20:23], v[136:139], v[180:183], v[20:23]
	v_mfma_f32_16x16x32_bf16 v[76:79], v[128:131], v[212:215], v[76:79]
	v_mfma_f32_16x16x32_bf16 v[12:15], v[136:139], v[212:215], v[12:15]
	v_mfma_f32_16x16x32_bf16 v[72:75], v[128:131], v[220:223], v[72:75]
	v_mfma_f32_16x16x32_bf16 v[4:7], v[136:139], v[220:223], v[4:7]
	v_mfma_f32_16x16x32_bf16 v[92:95], v[132:135], v[176:179], v[92:95]
	v_mfma_f32_16x16x32_bf16 v[28:31], v[140:143], v[176:179], v[28:31]
	v_mfma_f32_16x16x32_bf16 v[84:87], v[132:135], v[184:187], v[84:87]
	v_mfma_f32_16x16x32_bf16 v[20:23], v[140:143], v[184:187], v[20:23]
	v_mfma_f32_16x16x32_bf16 v[76:79], v[132:135], v[216:219], v[76:79]
	v_mfma_f32_16x16x32_bf16 v[12:15], v[140:143], v[216:219], v[12:15]
	v_mfma_f32_16x16x32_bf16 v[72:75], v[132:135], v[224:227], v[72:75]
	v_mfma_f32_16x16x32_bf16 v[4:7], v[140:143], v[224:227], v[4:7]
	s_setprio 0
	s_setprio 1
	v_mfma_f32_16x16x32_bf16 v[88:91], v[144:147], v[172:175], v[88:91]
	v_mfma_f32_16x16x32_bf16 v[24:27], v[152:155], v[172:175], v[24:27]
	v_mfma_f32_16x16x32_bf16 v[80:83], v[144:147], v[180:183], v[80:83]
	v_mfma_f32_16x16x32_bf16 v[16:19], v[152:155], v[180:183], v[16:19]
	v_mfma_f32_16x16x32_bf16 v[68:71], v[144:147], v[212:215], v[68:71]
	v_mfma_f32_16x16x32_bf16 v[8:11], v[152:155], v[212:215], v[8:11]
	v_mfma_f32_16x16x32_bf16 v[64:67], v[144:147], v[220:223], v[64:67]
	v_mfma_f32_16x16x32_bf16 v[0:3], v[152:155], v[220:223], v[0:3]
	v_mfma_f32_16x16x32_bf16 v[88:91], v[148:151], v[176:179], v[88:91]
	v_mfma_f32_16x16x32_bf16 v[24:27], v[156:159], v[176:179], v[24:27]
	v_mfma_f32_16x16x32_bf16 v[80:83], v[148:151], v[184:187], v[80:83]
	v_mfma_f32_16x16x32_bf16 v[16:19], v[156:159], v[184:187], v[16:19]
	v_mfma_f32_16x16x32_bf16 v[68:71], v[148:151], v[216:219], v[68:71]
	v_mfma_f32_16x16x32_bf16 v[8:11], v[156:159], v[216:219], v[8:11]
	v_mfma_f32_16x16x32_bf16 v[64:67], v[148:151], v[224:227], v[64:67]
	v_mfma_f32_16x16x32_bf16 v[0:3], v[156:159], v[224:227], v[0:3]
	s_setprio 0
	s_barrier
	s_add_u32 s68, s68, 0x100
	s_addc_u32 s69, s69, 0
	s_add_u32 s4, s4, 0x100
	s_addc_u32 s5, s5, 0
	s_cmp_ge_i32 s52, s7
	s_mov_b32 s8, s52
	s_cbranch_scc0 .LBB0_48
	s_mov_b64 s[54:55], s[84:85]
	s_and_b64 vcc, exec, s[54:55]
	s_cbranch_vccz .LBB0_51

.LBB0_119:
	s_add_i32 s52, s53, 2
	s_add_u32 s54, s4, 0xfffc0080
	s_addc_u32 s55, s5, -1
	s_add_i32 s56, 0, 0x10000
	v_add_u32_e32 v76, s56, v96
	ds_read_b128 v[32:35], v76
	ds_read_b128 v[36:39], v76 offset:1024
	ds_read_b128 v[72:75], v76 offset:2048
	ds_read_b128 v[76:79], v76 offset:3072
	s_cmp_eq_u32 s76, s53
	s_cselect_b32 s73, s51, s55
	s_cselect_b32 s72, s50, s54
	s_cselect_b32 s55, s69, s91
	s_cselect_b32 s54, s68, s77
	s_add_i32 m0, s9, 0xc000
	ds_read_b128 v[84:87], v97
	ds_read_b128 v[98:101], v97 offset:1024
	ds_read_b128 v[102:105], v97 offset:2048
	ds_read_b128 v[106:109], v97 offset:3072
	ds_read_b128 v[110:113], v97 offset:4096
	ds_read_b128 v[114:117], v97 offset:5120
	ds_read_b128 v[118:121], v97 offset:6144
	ds_read_b128 v[122:125], v97 offset:7168
	global_load_lds_dwordx4 v82, s[4:5]
	s_add_i32 m0, s9, 0xe000
	s_nop 0
	global_load_lds_dwordx4 v80, s[4:5]
	s_waitcnt vmcnt(6)
	s_waitcnt lgkmcnt(0)
	s_barrier
	s_setprio 1
	s_waitcnt lgkmcnt(0)
	v_mfma_f32_16x16x32_bf16 v[68:71], v[32:35], v[84:87], v[68:71]
	v_mfma_f32_16x16x32_bf16 v[64:67], v[72:75], v[84:87], v[64:67]
	v_mfma_f32_16x16x32_bf16 v[60:63], v[32:35], v[102:105], v[60:63]
	v_mfma_f32_16x16x32_bf16 v[56:59], v[72:75], v[102:105], v[56:59]
	v_mfma_f32_16x16x32_bf16 v[52:55], v[32:35], v[110:113], v[52:55]
	v_mfma_f32_16x16x32_bf16 v[48:51], v[72:75], v[110:113], v[48:51]
	v_mfma_f32_16x16x32_bf16 v[44:47], v[32:35], v[118:121], v[44:47]
	v_mfma_f32_16x16x32_bf16 v[40:43], v[72:75], v[118:121], v[40:43]
	v_mfma_f32_16x16x32_bf16 v[68:71], v[36:39], v[98:101], v[68:71]
	v_mfma_f32_16x16x32_bf16 v[64:67], v[76:79], v[98:101], v[64:67]
	v_mfma_f32_16x16x32_bf16 v[60:63], v[36:39], v[106:109], v[60:63]
	v_mfma_f32_16x16x32_bf16 v[56:59], v[76:79], v[106:109], v[56:59]
	v_mfma_f32_16x16x32_bf16 v[52:55], v[36:39], v[114:117], v[52:55]
	v_mfma_f32_16x16x32_bf16 v[48:51], v[76:79], v[114:117], v[48:51]
	v_mfma_f32_16x16x32_bf16 v[44:47], v[36:39], v[122:125], v[44:47]
	v_mfma_f32_16x16x32_bf16 v[40:43], v[76:79], v[122:125], v[40:43]
	s_setprio 0
	s_barrier
	s_add_i32 s53, s56, s8
	s_mov_b32 m0, s53
	ds_read_b128 v[84:87], v97 offset:16384
	ds_read_b128 v[98:101], v97 offset:17408
	ds_read_b128 v[102:105], v97 offset:18432
	ds_read_b128 v[106:109], v97 offset:19456
	ds_read_b128 v[110:113], v97 offset:20480
	ds_read_b128 v[114:117], v97 offset:21504
	ds_read_b128 v[118:121], v97 offset:22528
	ds_read_b128 v[122:125], v97 offset:23552
	global_load_lds_dwordx4 v164, s[54:55]
	s_add_i32 m0, s53, 0x2000
	s_nop 0
	global_load_lds_dwordx4 v152, s[54:55]
	s_mov_b32 m0, s9
	s_nop 0
	global_load_lds_dwordx4 v164, s[72:73]
	s_mov_b32 m0, s13
	s_nop 0
	global_load_lds_dwordx4 v152, s[72:73]
	s_waitcnt vmcnt(6)
	s_waitcnt lgkmcnt(0)
	s_barrier
	s_setprio 1
	s_waitcnt lgkmcnt(0)
	v_mfma_f32_16x16x32_bf16 v[28:31], v[32:35], v[84:87], v[28:31]
	v_mfma_f32_16x16x32_bf16 v[24:27], v[72:75], v[84:87], v[24:27]
	v_mfma_f32_16x16x32_bf16 v[20:23], v[32:35], v[102:105], v[20:23]
	v_mfma_f32_16x16x32_bf16 v[16:19], v[72:75], v[102:105], v[16:19]
	v_mfma_f32_16x16x32_bf16 v[12:15], v[32:35], v[110:113], v[12:15]
	v_mfma_f32_16x16x32_bf16 v[8:11], v[72:75], v[110:113], v[8:11]
	v_mfma_f32_16x16x32_bf16 v[4:7], v[32:35], v[118:121], v[4:7]
	v_mfma_f32_16x16x32_bf16 v[0:3], v[72:75], v[118:121], v[0:3]
	v_mfma_f32_16x16x32_bf16 v[28:31], v[36:39], v[98:101], v[28:31]
	v_mfma_f32_16x16x32_bf16 v[24:27], v[76:79], v[98:101], v[24:27]
	v_mfma_f32_16x16x32_bf16 v[20:23], v[36:39], v[106:109], v[20:23]
	v_mfma_f32_16x16x32_bf16 v[16:19], v[76:79], v[106:109], v[16:19]
	v_mfma_f32_16x16x32_bf16 v[12:15], v[36:39], v[114:117], v[12:15]
	v_mfma_f32_16x16x32_bf16 v[8:11], v[76:79], v[114:117], v[8:11]
	v_mfma_f32_16x16x32_bf16 v[4:7], v[36:39], v[122:125], v[4:7]
	v_mfma_f32_16x16x32_bf16 v[0:3], v[76:79], v[122:125], v[0:3]
	s_setprio 0
	s_barrier
	s_add_i32 s53, 0, 0x18000
	v_add_u32_e32 v76, s53, v96
	ds_read_b128 v[32:35], v76
	ds_read_b128 v[36:39], v76 offset:1024
	ds_read_b128 v[72:75], v76 offset:2048
	ds_read_b128 v[76:79], v76 offset:3072
	s_add_u32 s98, s72, 0x40000
	s_addc_u32 s99, s73, 0
	s_mov_b32 m0, s89
	s_nop 0
	ds_read_b128 v[84:87], v97 offset:32768
	ds_read_b128 v[98:101], v97 offset:33792
	ds_read_b128 v[102:105], v97 offset:34816
	ds_read_b128 v[106:109], v97 offset:35840
	ds_read_b128 v[110:113], v97 offset:36864
	ds_read_b128 v[114:117], v97 offset:37888
	ds_read_b128 v[118:121], v97 offset:38912
	ds_read_b128 v[122:125], v97 offset:39936
	global_load_lds_dwordx4 v164, s[98:99]
	s_mov_b32 m0, s3
	s_nop 0
	global_load_lds_dwordx4 v152, s[98:99]
	s_waitcnt vmcnt(6)
	s_waitcnt lgkmcnt(0)
	s_barrier
	s_setprio 1
	s_waitcnt lgkmcnt(0)
	v_mfma_f32_16x16x32_bf16 v[68:71], v[32:35], v[84:87], v[68:71]
	v_mfma_f32_16x16x32_bf16 v[64:67], v[72:75], v[84:87], v[64:67]
	v_mfma_f32_16x16x32_bf16 v[60:63], v[32:35], v[102:105], v[60:63]
	v_mfma_f32_16x16x32_bf16 v[56:59], v[72:75], v[102:105], v[56:59]
	v_mfma_f32_16x16x32_bf16 v[52:55], v[32:35], v[110:113], v[52:55]
	v_mfma_f32_16x16x32_bf16 v[48:51], v[72:75], v[110:113], v[48:51]
	v_mfma_f32_16x16x32_bf16 v[44:47], v[32:35], v[118:121], v[44:47]
	v_mfma_f32_16x16x32_bf16 v[40:43], v[72:75], v[118:121], v[40:43]
	v_mfma_f32_16x16x32_bf16 v[68:71], v[36:39], v[98:101], v[68:71]
	v_mfma_f32_16x16x32_bf16 v[64:67], v[76:79], v[98:101], v[64:67]
	v_mfma_f32_16x16x32_bf16 v[60:63], v[36:39], v[106:109], v[60:63]
	v_mfma_f32_16x16x32_bf16 v[56:59], v[76:79], v[106:109], v[56:59]
	v_mfma_f32_16x16x32_bf16 v[52:55], v[36:39], v[114:117], v[52:55]
	v_mfma_f32_16x16x32_bf16 v[48:51], v[76:79], v[114:117], v[48:51]
	v_mfma_f32_16x16x32_bf16 v[44:47], v[36:39], v[122:125], v[44:47]
	v_mfma_f32_16x16x32_bf16 v[40:43], v[76:79], v[122:125], v[40:43]
	s_setprio 0
	s_barrier
	s_add_i32 s53, s53, s8
	s_add_i32 m0, s53, 0xffffff80
	ds_read_b128 v[84:87], v97 offset:49152
	ds_read_b128 v[98:101], v97 offset:50176
	ds_read_b128 v[102:105], v97 offset:51200
	ds_read_b128 v[106:109], v97 offset:52224
	ds_read_b128 v[110:113], v97 offset:53248
	ds_read_b128 v[114:117], v97 offset:54272
	ds_read_b128 v[118:121], v97 offset:55296
	ds_read_b128 v[122:125], v97 offset:56320
	global_load_lds_dwordx4 v164, s[54:55] offset:128
	s_add_i32 m0, s53, 0x1f80
	s_nop 0
	global_load_lds_dwordx4 v152, s[54:55] offset:128
	s_add_i32 m0, s97, 0xffffff80
	s_nop 0
	global_load_lds_dwordx4 v164, s[72:73] offset:128
	s_add_i32 m0, s10, 0xffffff80
	s_nop 0
	global_load_lds_dwordx4 v152, s[72:73] offset:128
	s_waitcnt vmcnt(6)
	s_waitcnt lgkmcnt(0)
	s_barrier
	s_setprio 1
	s_waitcnt lgkmcnt(0)
	v_mfma_f32_16x16x32_bf16 v[28:31], v[32:35], v[84:87], v[28:31]
	v_mfma_f32_16x16x32_bf16 v[24:27], v[72:75], v[84:87], v[24:27]
	v_mfma_f32_16x16x32_bf16 v[20:23], v[32:35], v[102:105], v[20:23]
	v_mfma_f32_16x16x32_bf16 v[16:19], v[72:75], v[102:105], v[16:19]
	v_mfma_f32_16x16x32_bf16 v[12:15], v[32:35], v[110:113], v[12:15]
	v_mfma_f32_16x16x32_bf16 v[8:11], v[72:75], v[110:113], v[8:11]
	v_mfma_f32_16x16x32_bf16 v[4:7], v[32:35], v[118:121], v[4:7]
	v_mfma_f32_16x16x32_bf16 v[0:3], v[72:75], v[118:121], v[0:3]
	v_mfma_f32_16x16x32_bf16 v[28:31], v[36:39], v[98:101], v[28:31]
	v_mfma_f32_16x16x32_bf16 v[24:27], v[76:79], v[98:101], v[24:27]
	v_mfma_f32_16x16x32_bf16 v[20:23], v[36:39], v[106:109], v[20:23]
	v_mfma_f32_16x16x32_bf16 v[16:19], v[76:79], v[106:109], v[16:19]
	v_mfma_f32_16x16x32_bf16 v[12:15], v[36:39], v[114:117], v[12:15]
	v_mfma_f32_16x16x32_bf16 v[8:11], v[76:79], v[114:117], v[8:11]
	v_mfma_f32_16x16x32_bf16 v[4:7], v[36:39], v[122:125], v[4:7]
	v_mfma_f32_16x16x32_bf16 v[0:3], v[76:79], v[122:125], v[0:3]
	s_setprio 0
	s_barrier
	s_add_u32 s77, s77, 0x100
	s_addc_u32 s91, s91, 0
	s_add_u32 s4, s4, 0x100
	s_addc_u32 s5, s5, 0
	s_cmp_ge_i32 s52, s47
	s_mov_b32 s53, s52
	s_cbranch_scc0 .LBB0_119
	s_branch .LBB0_121

.LBB0_151:
	s_add_i32 s53, s52, 2
	s_add_u32 s54, s68, 0xfffc0080
	s_addc_u32 s55, s69, -1
	s_add_i32 s56, 0, 0x10000
	s_cmp_eq_u32 s33, s52
	s_cselect_b32 s73, s43, s55
	s_cselect_b32 s72, s42, s54
	s_cselect_b32 s71, s47, s51
	s_cselect_b32 s70, s46, s35
	s_add_i32 s52, 0, 0x14000
	v_add_u32_e32 v60, s56, v162
	v_add_u32_e32 v166, s52, v162
	ds_read_b128 v[32:35], v60
	ds_read_b128 v[36:39], v60 offset:1024
	ds_read_b128 v[40:43], v60 offset:2048
	ds_read_b128 v[60:63], v60 offset:3072
	ds_read_b128 v[64:67], v166
	ds_read_b128 v[68:71], v166 offset:1024
	ds_read_b128 v[158:161], v166 offset:2048
	ds_read_b128 v[166:169], v166 offset:3072
	s_add_i32 m0, s5, 0xc000
	ds_read_b128 v[170:173], v163
	ds_read_b128 v[174:177], v163 offset:1024
	ds_read_b128 v[178:181], v163 offset:2048
	ds_read_b128 v[182:185], v163 offset:3072
	ds_read_b128 v[186:189], v163 offset:4096
	ds_read_b128 v[212:215], v163 offset:5120
	ds_read_b128 v[216:219], v163 offset:6144
	ds_read_b128 v[220:223], v163 offset:7168
	global_load_lds_dwordx4 v156, s[68:69]
	s_add_i32 m0, s5, 0xe000
	s_nop 0
	global_load_lds_dwordx4 v154, s[68:69]
	s_waitcnt vmcnt(8)
	s_waitcnt lgkmcnt(0)
	s_barrier
	s_setprio 1
	s_waitcnt lgkmcnt(0)
	v_mfma_f32_16x16x32_bf16 v[144:147], v[32:35], v[170:173], v[144:147]
	v_mfma_f32_16x16x32_bf16 v[136:139], v[40:43], v[170:173], v[136:139]
	v_mfma_f32_16x16x32_bf16 v[128:131], v[32:35], v[178:181], v[128:131]
	v_mfma_f32_16x16x32_bf16 v[120:123], v[40:43], v[178:181], v[120:123]
	v_mfma_f32_16x16x32_bf16 v[112:115], v[32:35], v[186:189], v[112:115]
	v_mfma_f32_16x16x32_bf16 v[104:107], v[40:43], v[186:189], v[104:107]
	v_mfma_f32_16x16x32_bf16 v[96:99], v[32:35], v[216:219], v[96:99]
	v_mfma_f32_16x16x32_bf16 v[88:91], v[40:43], v[216:219], v[88:91]
	v_mfma_f32_16x16x32_bf16 v[144:147], v[36:39], v[174:177], v[144:147]
	v_mfma_f32_16x16x32_bf16 v[136:139], v[60:63], v[174:177], v[136:139]
	v_mfma_f32_16x16x32_bf16 v[128:131], v[36:39], v[182:185], v[128:131]
	v_mfma_f32_16x16x32_bf16 v[120:123], v[60:63], v[182:185], v[120:123]
	v_mfma_f32_16x16x32_bf16 v[112:115], v[36:39], v[212:215], v[112:115]
	v_mfma_f32_16x16x32_bf16 v[104:107], v[60:63], v[212:215], v[104:107]
	v_mfma_f32_16x16x32_bf16 v[96:99], v[36:39], v[220:223], v[96:99]
	v_mfma_f32_16x16x32_bf16 v[88:91], v[60:63], v[220:223], v[88:91]
	s_setprio 0
	s_setprio 1
	v_mfma_f32_16x16x32_bf16 v[148:151], v[64:67], v[170:173], v[148:151]
	v_mfma_f32_16x16x32_bf16 v[140:143], v[158:161], v[170:173], v[140:143]
	v_mfma_f32_16x16x32_bf16 v[132:135], v[64:67], v[178:181], v[132:135]
	v_mfma_f32_16x16x32_bf16 v[124:127], v[158:161], v[178:181], v[124:127]
	v_mfma_f32_16x16x32_bf16 v[116:119], v[64:67], v[186:189], v[116:119]
	v_mfma_f32_16x16x32_bf16 v[108:111], v[158:161], v[186:189], v[108:111]
	v_mfma_f32_16x16x32_bf16 v[100:103], v[64:67], v[216:219], v[100:103]
	v_mfma_f32_16x16x32_bf16 v[92:95], v[158:161], v[216:219], v[92:95]
	v_mfma_f32_16x16x32_bf16 v[148:151], v[68:71], v[174:177], v[148:151]
	v_mfma_f32_16x16x32_bf16 v[140:143], v[166:169], v[174:177], v[140:143]
	v_mfma_f32_16x16x32_bf16 v[132:135], v[68:71], v[182:185], v[132:135]
	v_mfma_f32_16x16x32_bf16 v[124:127], v[166:169], v[182:185], v[124:127]
	v_mfma_f32_16x16x32_bf16 v[116:119], v[68:71], v[212:215], v[116:119]
	v_mfma_f32_16x16x32_bf16 v[108:111], v[166:169], v[212:215], v[108:111]
	v_mfma_f32_16x16x32_bf16 v[100:103], v[68:71], v[220:223], v[100:103]
	v_mfma_f32_16x16x32_bf16 v[92:95], v[166:169], v[220:223], v[92:95]
	s_setprio 0
	s_barrier
	s_add_i32 s54, s56, s4
	s_mov_b32 m0, s54
	ds_read_b128 v[170:173], v163 offset:16384
	ds_read_b128 v[174:177], v163 offset:17408
	ds_read_b128 v[178:181], v163 offset:18432
	ds_read_b128 v[182:185], v163 offset:19456
	ds_read_b128 v[186:189], v163 offset:20480
	ds_read_b128 v[212:215], v163 offset:21504
	ds_read_b128 v[216:219], v163 offset:22528
	ds_read_b128 v[220:223], v163 offset:23552
	global_load_lds_dwordx4 v164, s[70:71]
	s_add_i32 m0, s54, 0x2000
	s_add_u32 s54, s70, 0x40000
	s_addc_u32 s55, s71, 0
	s_add_i32 s52, s52, s4
	global_load_lds_dwordx4 v152, s[70:71]
	s_mov_b32 m0, s52
	s_nop 0
	global_load_lds_dwordx4 v164, s[54:55]
	s_add_i32 m0, s52, 0x2000
	s_nop 0
	global_load_lds_dwordx4 v152, s[54:55]
	s_mov_b32 m0, s5
	s_nop 0
	global_load_lds_dwordx4 v164, s[72:73]
	s_mov_b32 m0, s12
	s_nop 0
	global_load_lds_dwordx4 v152, s[72:73]
	s_waitcnt vmcnt(8)
	s_waitcnt lgkmcnt(0)
	s_barrier
	s_setprio 1
	s_waitcnt lgkmcnt(0)
	v_mfma_f32_16x16x32_bf16 v[80:83], v[32:35], v[170:173], v[80:83]
	v_mfma_f32_16x16x32_bf16 v[72:75], v[40:43], v[170:173], v[72:75]
	v_mfma_f32_16x16x32_bf16 v[52:55], v[32:35], v[178:181], v[52:55]
	v_mfma_f32_16x16x32_bf16 v[44:47], v[40:43], v[178:181], v[44:47]
	v_mfma_f32_16x16x32_bf16 v[24:27], v[32:35], v[186:189], v[24:27]
	v_mfma_f32_16x16x32_bf16 v[16:19], v[40:43], v[186:189], v[16:19]
	v_mfma_f32_16x16x32_bf16 v[8:11], v[32:35], v[216:219], v[8:11]
	v_mfma_f32_16x16x32_bf16 v[0:3], v[40:43], v[216:219], v[0:3]
	v_mfma_f32_16x16x32_bf16 v[80:83], v[36:39], v[174:177], v[80:83]
	v_mfma_f32_16x16x32_bf16 v[72:75], v[60:63], v[174:177], v[72:75]
	v_mfma_f32_16x16x32_bf16 v[52:55], v[36:39], v[182:185], v[52:55]
	v_mfma_f32_16x16x32_bf16 v[44:47], v[60:63], v[182:185], v[44:47]
	v_mfma_f32_16x16x32_bf16 v[24:27], v[36:39], v[212:215], v[24:27]
	v_mfma_f32_16x16x32_bf16 v[16:19], v[60:63], v[212:215], v[16:19]
	v_mfma_f32_16x16x32_bf16 v[8:11], v[36:39], v[220:223], v[8:11]
	v_mfma_f32_16x16x32_bf16 v[0:3], v[60:63], v[220:223], v[0:3]
	s_setprio 0
	s_setprio 1
	v_mfma_f32_16x16x32_bf16 v[48:51], v[158:161], v[178:181], v[48:51]
	v_mfma_f32_16x16x32_bf16 v[28:31], v[64:67], v[186:189], v[28:31]
	v_mfma_f32_16x16x32_bf16 v[20:23], v[158:161], v[186:189], v[20:23]
	v_mfma_f32_16x16x32_bf16 v[12:15], v[64:67], v[216:219], v[12:15]
	v_mfma_f32_16x16x32_bf16 v[4:7], v[158:161], v[216:219], v[4:7]
	v_mfma_f32_16x16x32_bf16 v[32:35], v[64:67], v[170:173], v[84:87]
	v_mfma_f32_16x16x32_bf16 v[36:39], v[158:161], v[170:173], v[76:79]
	v_mfma_f32_16x16x32_bf16 v[40:43], v[64:67], v[178:181], v[56:59]
	v_mfma_f32_16x16x32_bf16 v[48:51], v[166:169], v[182:185], v[48:51]
	v_mfma_f32_16x16x32_bf16 v[28:31], v[68:71], v[212:215], v[28:31]
	v_mfma_f32_16x16x32_bf16 v[20:23], v[166:169], v[212:215], v[20:23]
	v_mfma_f32_16x16x32_bf16 v[12:15], v[68:71], v[220:223], v[12:15]
	v_mfma_f32_16x16x32_bf16 v[4:7], v[166:169], v[220:223], v[4:7]
	v_mfma_f32_16x16x32_bf16 v[32:35], v[68:71], v[174:177], v[32:35]
	v_mfma_f32_16x16x32_bf16 v[36:39], v[166:169], v[174:177], v[36:39]
	v_mfma_f32_16x16x32_bf16 v[40:43], v[68:71], v[182:185], v[40:43]
	s_setprio 0
	s_barrier
	s_add_i32 s52, 0, 0x18000
	s_add_i32 s56, 0, 0x1c000
	v_add_u32_e32 v68, s52, v162
	v_add_u32_e32 v76, s56, v162
	ds_read_b128 v[56:59], v68
	ds_read_b128 v[60:63], v68 offset:1024
	ds_read_b128 v[64:67], v68 offset:2048
	ds_read_b128 v[68:71], v68 offset:3072
	ds_read_b128 v[158:161], v76
	ds_read_b128 v[166:169], v76 offset:1024
	ds_read_b128 v[170:173], v76 offset:2048
	ds_read_b128 v[174:177], v76 offset:3072
	s_add_u32 s54, s72, 0x40000
	s_addc_u32 s55, s73, 0
	s_mov_b32 m0, s13
	s_nop 0
	ds_read_b128 v[76:79], v163 offset:32768
	ds_read_b128 v[84:87], v163 offset:33792
	ds_read_b128 v[178:181], v163 offset:34816
	ds_read_b128 v[182:185], v163 offset:35840
	ds_read_b128 v[186:189], v163 offset:36864
	ds_read_b128 v[212:215], v163 offset:37888
	ds_read_b128 v[216:219], v163 offset:38912
	ds_read_b128 v[220:223], v163 offset:39936
	global_load_lds_dwordx4 v164, s[54:55]
	s_mov_b32 m0, s11
	s_nop 0
	global_load_lds_dwordx4 v152, s[54:55]
	s_waitcnt vmcnt(8)
	s_waitcnt lgkmcnt(0)
	s_barrier
	s_setprio 1
	s_waitcnt lgkmcnt(0)
	v_mfma_f32_16x16x32_bf16 v[144:147], v[56:59], v[76:79], v[144:147]
	v_mfma_f32_16x16x32_bf16 v[136:139], v[64:67], v[76:79], v[136:139]
	v_mfma_f32_16x16x32_bf16 v[128:131], v[56:59], v[178:181], v[128:131]
	v_mfma_f32_16x16x32_bf16 v[120:123], v[64:67], v[178:181], v[120:123]
	v_mfma_f32_16x16x32_bf16 v[112:115], v[56:59], v[186:189], v[112:115]
	v_mfma_f32_16x16x32_bf16 v[104:107], v[64:67], v[186:189], v[104:107]
	v_mfma_f32_16x16x32_bf16 v[96:99], v[56:59], v[216:219], v[96:99]
	v_mfma_f32_16x16x32_bf16 v[88:91], v[64:67], v[216:219], v[88:91]
	v_mfma_f32_16x16x32_bf16 v[144:147], v[60:63], v[84:87], v[144:147]
	v_mfma_f32_16x16x32_bf16 v[136:139], v[68:71], v[84:87], v[136:139]
	v_mfma_f32_16x16x32_bf16 v[128:131], v[60:63], v[182:185], v[128:131]
	v_mfma_f32_16x16x32_bf16 v[120:123], v[68:71], v[182:185], v[120:123]
	v_mfma_f32_16x16x32_bf16 v[112:115], v[60:63], v[212:215], v[112:115]
	v_mfma_f32_16x16x32_bf16 v[104:107], v[68:71], v[212:215], v[104:107]
	v_mfma_f32_16x16x32_bf16 v[96:99], v[60:63], v[220:223], v[96:99]
	v_mfma_f32_16x16x32_bf16 v[88:91], v[68:71], v[220:223], v[88:91]
	s_setprio 0
	s_setprio 1
	v_mfma_f32_16x16x32_bf16 v[148:151], v[158:161], v[76:79], v[148:151]
	v_mfma_f32_16x16x32_bf16 v[76:79], v[170:173], v[76:79], v[140:143]
	v_mfma_f32_16x16x32_bf16 v[140:143], v[174:177], v[84:87], v[76:79]
	v_mfma_f32_16x16x32_bf16 v[76:79], v[158:161], v[178:181], v[132:135]
	v_mfma_f32_16x16x32_bf16 v[132:135], v[166:169], v[182:185], v[76:79]
	v_mfma_f32_16x16x32_bf16 v[76:79], v[170:173], v[178:181], v[124:127]
	v_mfma_f32_16x16x32_bf16 v[124:127], v[174:177], v[182:185], v[76:79]
	v_mfma_f32_16x16x32_bf16 v[76:79], v[158:161], v[186:189], v[116:119]
	v_mfma_f32_16x16x32_bf16 v[116:119], v[166:169], v[212:215], v[76:79]
	v_mfma_f32_16x16x32_bf16 v[76:79], v[170:173], v[186:189], v[108:111]
	v_mfma_f32_16x16x32_bf16 v[108:111], v[174:177], v[212:215], v[76:79]
	v_mfma_f32_16x16x32_bf16 v[76:79], v[158:161], v[216:219], v[100:103]
	v_mfma_f32_16x16x32_bf16 v[100:103], v[166:169], v[220:223], v[76:79]
	v_mfma_f32_16x16x32_bf16 v[76:79], v[170:173], v[216:219], v[92:95]
	v_mfma_f32_16x16x32_bf16 v[148:151], v[166:169], v[84:87], v[148:151]
	v_mfma_f32_16x16x32_bf16 v[92:95], v[174:177], v[220:223], v[76:79]
	s_setprio 0
	s_barrier
	s_add_i32 s52, s52, s4
	s_add_i32 m0, s52, 0xffffff80
	s_nop 0
	ds_read_b128 v[76:79], v163 offset:49152
	ds_read_b128 v[178:181], v163 offset:50176
	ds_read_b128 v[182:185], v163 offset:51200
	ds_read_b128 v[186:189], v163 offset:52224
	ds_read_b128 v[212:215], v163 offset:53248
	ds_read_b128 v[216:219], v163 offset:54272
	ds_read_b128 v[220:223], v163 offset:55296
	ds_read_b128 v[224:227], v163 offset:56320
	global_load_lds_dwordx4 v164, s[70:71] offset:128
	s_add_i32 m0, s52, 0x1f80
	s_add_u32 s54, s70, 0x40080
	s_addc_u32 s55, s71, 0
	s_add_i32 s52, s56, s4
	global_load_lds_dwordx4 v152, s[70:71] offset:128
	s_mov_b32 m0, s52
	s_nop 0
	global_load_lds_dwordx4 v164, s[54:55]
	s_add_i32 m0, s52, 0x2000
	s_nop 0
	global_load_lds_dwordx4 v152, s[54:55]
	s_add_i32 m0, s14, 0xffffff80
	s_nop 0
	global_load_lds_dwordx4 v164, s[72:73] offset:128
	s_add_i32 m0, s15, 0xffffff80
	s_nop 0
	global_load_lds_dwordx4 v152, s[72:73] offset:128
	s_waitcnt vmcnt(8)
	s_waitcnt lgkmcnt(0)
	s_barrier
	s_setprio 1
	s_waitcnt lgkmcnt(0)
	v_mfma_f32_16x16x32_bf16 v[80:83], v[56:59], v[76:79], v[80:83]
	v_mfma_f32_16x16x32_bf16 v[72:75], v[64:67], v[76:79], v[72:75]
	v_mfma_f32_16x16x32_bf16 v[52:55], v[56:59], v[182:185], v[52:55]
	v_mfma_f32_16x16x32_bf16 v[44:47], v[64:67], v[182:185], v[44:47]
	v_mfma_f32_16x16x32_bf16 v[24:27], v[56:59], v[212:215], v[24:27]
	v_mfma_f32_16x16x32_bf16 v[16:19], v[64:67], v[212:215], v[16:19]
	v_mfma_f32_16x16x32_bf16 v[8:11], v[56:59], v[220:223], v[8:11]
	v_mfma_f32_16x16x32_bf16 v[0:3], v[64:67], v[220:223], v[0:3]
	v_mfma_f32_16x16x32_bf16 v[80:83], v[60:63], v[178:181], v[80:83]
	v_mfma_f32_16x16x32_bf16 v[72:75], v[68:71], v[178:181], v[72:75]
	v_mfma_f32_16x16x32_bf16 v[52:55], v[60:63], v[186:189], v[52:55]
	v_mfma_f32_16x16x32_bf16 v[44:47], v[68:71], v[186:189], v[44:47]
	v_mfma_f32_16x16x32_bf16 v[24:27], v[60:63], v[216:219], v[24:27]
	v_mfma_f32_16x16x32_bf16 v[16:19], v[68:71], v[216:219], v[16:19]
	v_mfma_f32_16x16x32_bf16 v[8:11], v[60:63], v[224:227], v[8:11]
	v_mfma_f32_16x16x32_bf16 v[0:3], v[68:71], v[224:227], v[0:3]
	s_setprio 0
	s_setprio 1
	v_mfma_f32_16x16x32_bf16 v[32:35], v[158:161], v[76:79], v[32:35]
	v_mfma_f32_16x16x32_bf16 v[84:87], v[166:169], v[178:181], v[32:35]
	v_mfma_f32_16x16x32_bf16 v[32:35], v[170:173], v[76:79], v[36:39]
	v_mfma_f32_16x16x32_bf16 v[76:79], v[174:177], v[178:181], v[32:35]
	v_mfma_f32_16x16x32_bf16 v[32:35], v[158:161], v[182:185], v[40:43]
	v_mfma_f32_16x16x32_bf16 v[56:59], v[166:169], v[186:189], v[32:35]
	v_mfma_f32_16x16x32_bf16 v[32:35], v[170:173], v[182:185], v[48:51]
	v_mfma_f32_16x16x32_bf16 v[28:31], v[158:161], v[212:215], v[28:31]
	v_mfma_f32_16x16x32_bf16 v[20:23], v[170:173], v[212:215], v[20:23]
	v_mfma_f32_16x16x32_bf16 v[12:15], v[158:161], v[220:223], v[12:15]
	v_mfma_f32_16x16x32_bf16 v[4:7], v[170:173], v[220:223], v[4:7]
	v_mfma_f32_16x16x32_bf16 v[48:51], v[174:177], v[186:189], v[32:35]
	v_mfma_f32_16x16x32_bf16 v[28:31], v[166:169], v[216:219], v[28:31]
	v_mfma_f32_16x16x32_bf16 v[20:23], v[174:177], v[216:219], v[20:23]
	v_mfma_f32_16x16x32_bf16 v[12:15], v[166:169], v[224:227], v[12:15]
	v_mfma_f32_16x16x32_bf16 v[4:7], v[174:177], v[224:227], v[4:7]
	s_setprio 0
	s_barrier
	s_add_u32 s35, s35, 0x100
	s_addc_u32 s51, s51, 0
	s_add_u32 s68, s68, 0x100
	s_addc_u32 s69, s69, 0
	s_cmp_ge_i32 s53, s9
	s_mov_b32 s52, s53
	s_cbranch_scc0 .LBB0_151
	s_branch .LBB0_153

.LBB0_181:
	s_add_i32 s52, s46, 2
	s_add_u32 s53, s42, 0xfff00080
	s_addc_u32 s47, s43, -1
	s_add_i32 s56, 0, 0x10000
	v_add_u32_e32 v88, s56, v74
	ds_read_b128 v[76:79], v88
	ds_read_b128 v[80:83], v88 offset:1024
	ds_read_b128 v[84:87], v88 offset:2048
	ds_read_b128 v[88:91], v88 offset:3072
	s_cmp_eq_u32 s7, s46
	s_cselect_b32 s46, s34, s53
	s_cselect_b32 s47, s35, s47
	s_cselect_b32 s55, s15, vcc_hi
	s_cselect_b32 s54, s14, vcc_lo
	s_mov_b64 s[98:99], s[46:47]
	s_add_i32 m0, s68, 0xc000
	ds_read_b128 v[92:95], v75
	ds_read_b128 v[96:99], v75 offset:1024
	ds_read_b128 v[100:103], v75 offset:2048
	ds_read_b128 v[104:107], v75 offset:3072
	ds_read_b128 v[108:111], v75 offset:4096
	ds_read_b128 v[112:115], v75 offset:5120
	ds_read_b128 v[116:119], v75 offset:6144
	ds_read_b128 v[120:123], v75 offset:7168
	global_load_lds_dwordx4 v72, s[42:43]
	s_add_i32 m0, s68, 0xe000
	s_nop 0
	global_load_lds_dwordx4 v70, s[42:43]
	s_waitcnt vmcnt(6)
	s_waitcnt lgkmcnt(0)
	s_barrier
	s_setprio 1
	s_waitcnt lgkmcnt(0)
	v_mfma_f32_16x16x32_bf16 v[60:63], v[76:79], v[92:95], v[60:63]
	v_mfma_f32_16x16x32_bf16 v[56:59], v[84:87], v[92:95], v[56:59]
	v_mfma_f32_16x16x32_bf16 v[52:55], v[76:79], v[100:103], v[52:55]
	v_mfma_f32_16x16x32_bf16 v[48:51], v[84:87], v[100:103], v[48:51]
	v_mfma_f32_16x16x32_bf16 v[44:47], v[76:79], v[108:111], v[44:47]
	v_mfma_f32_16x16x32_bf16 v[40:43], v[84:87], v[108:111], v[40:43]
	v_mfma_f32_16x16x32_bf16 v[36:39], v[76:79], v[116:119], v[36:39]
	v_mfma_f32_16x16x32_bf16 v[32:35], v[84:87], v[116:119], v[32:35]
	v_mfma_f32_16x16x32_bf16 v[60:63], v[80:83], v[96:99], v[60:63]
	v_mfma_f32_16x16x32_bf16 v[56:59], v[88:91], v[96:99], v[56:59]
	v_mfma_f32_16x16x32_bf16 v[52:55], v[80:83], v[104:107], v[52:55]
	v_mfma_f32_16x16x32_bf16 v[48:51], v[88:91], v[104:107], v[48:51]
	v_mfma_f32_16x16x32_bf16 v[44:47], v[80:83], v[112:115], v[44:47]
	v_mfma_f32_16x16x32_bf16 v[40:43], v[88:91], v[112:115], v[40:43]
	v_mfma_f32_16x16x32_bf16 v[36:39], v[80:83], v[120:123], v[36:39]
	v_mfma_f32_16x16x32_bf16 v[32:35], v[88:91], v[120:123], v[32:35]
	s_setprio 0
	s_barrier
	s_add_i32 s53, s56, s51
	s_mov_b32 m0, s53
	ds_read_b128 v[92:95], v75 offset:16384
	ds_read_b128 v[96:99], v75 offset:17408
	ds_read_b128 v[100:103], v75 offset:18432
	ds_read_b128 v[104:107], v75 offset:19456
	ds_read_b128 v[108:111], v75 offset:20480
	ds_read_b128 v[112:115], v75 offset:21504
	ds_read_b128 v[116:119], v75 offset:22528
	ds_read_b128 v[120:123], v75 offset:23552
	global_load_lds_dwordx4 v164, s[54:55]
	s_add_i32 m0, s53, 0x2000
	s_nop 0
	global_load_lds_dwordx4 v68, s[54:55]
	s_mov_b32 m0, s68
	s_nop 0
	global_load_lds_dwordx4 v64, s[98:99]
	s_mov_b32 m0, s72
	s_nop 0
	global_load_lds_dwordx4 v66, s[98:99]
	s_waitcnt vmcnt(6)
	s_waitcnt lgkmcnt(0)
	s_barrier
	s_setprio 1
	s_waitcnt lgkmcnt(0)
	v_mfma_f32_16x16x32_bf16 v[28:31], v[76:79], v[92:95], v[28:31]
	v_mfma_f32_16x16x32_bf16 v[24:27], v[84:87], v[92:95], v[24:27]
	v_mfma_f32_16x16x32_bf16 v[20:23], v[76:79], v[100:103], v[20:23]
	v_mfma_f32_16x16x32_bf16 v[16:19], v[84:87], v[100:103], v[16:19]
	v_mfma_f32_16x16x32_bf16 v[12:15], v[76:79], v[108:111], v[12:15]
	v_mfma_f32_16x16x32_bf16 v[8:11], v[84:87], v[108:111], v[8:11]
	v_mfma_f32_16x16x32_bf16 v[4:7], v[76:79], v[116:119], v[4:7]
	v_mfma_f32_16x16x32_bf16 v[0:3], v[84:87], v[116:119], v[0:3]
	v_mfma_f32_16x16x32_bf16 v[28:31], v[80:83], v[96:99], v[28:31]
	v_mfma_f32_16x16x32_bf16 v[24:27], v[88:91], v[96:99], v[24:27]
	v_mfma_f32_16x16x32_bf16 v[20:23], v[80:83], v[104:107], v[20:23]
	v_mfma_f32_16x16x32_bf16 v[16:19], v[88:91], v[104:107], v[16:19]
	v_mfma_f32_16x16x32_bf16 v[12:15], v[80:83], v[112:115], v[12:15]
	v_mfma_f32_16x16x32_bf16 v[8:11], v[88:91], v[112:115], v[8:11]
	v_mfma_f32_16x16x32_bf16 v[4:7], v[80:83], v[120:123], v[4:7]
	v_mfma_f32_16x16x32_bf16 v[0:3], v[88:91], v[120:123], v[0:3]
	s_setprio 0
	s_barrier
	s_add_i32 s53, 0, 0x18000
	v_add_u32_e32 v88, s53, v74
	ds_read_b128 v[76:79], v88
	ds_read_b128 v[80:83], v88 offset:1024
	ds_read_b128 v[84:87], v88 offset:2048
	ds_read_b128 v[88:91], v88 offset:3072
	s_add_u32 s46, s46, 0x100000
	s_addc_u32 s47, s47, 0
	s_mov_b32 m0, s73
	s_nop 0
	ds_read_b128 v[92:95], v75 offset:32768
	ds_read_b128 v[96:99], v75 offset:33792
	ds_read_b128 v[100:103], v75 offset:34816
	ds_read_b128 v[104:107], v75 offset:35840
	ds_read_b128 v[108:111], v75 offset:36864
	ds_read_b128 v[112:115], v75 offset:37888
	ds_read_b128 v[116:119], v75 offset:38912
	ds_read_b128 v[120:123], v75 offset:39936
	global_load_lds_dwordx4 v64, s[46:47]
	s_mov_b32 m0, s76
	s_nop 0
	global_load_lds_dwordx4 v66, s[46:47]
	s_waitcnt vmcnt(6)
	s_waitcnt lgkmcnt(0)
	s_barrier
	s_setprio 1
	s_waitcnt lgkmcnt(0)
	v_mfma_f32_16x16x32_bf16 v[60:63], v[76:79], v[92:95], v[60:63]
	v_mfma_f32_16x16x32_bf16 v[56:59], v[84:87], v[92:95], v[56:59]
	v_mfma_f32_16x16x32_bf16 v[52:55], v[76:79], v[100:103], v[52:55]
	v_mfma_f32_16x16x32_bf16 v[48:51], v[84:87], v[100:103], v[48:51]
	v_mfma_f32_16x16x32_bf16 v[44:47], v[76:79], v[108:111], v[44:47]
	v_mfma_f32_16x16x32_bf16 v[40:43], v[84:87], v[108:111], v[40:43]
	v_mfma_f32_16x16x32_bf16 v[36:39], v[76:79], v[116:119], v[36:39]
	v_mfma_f32_16x16x32_bf16 v[32:35], v[84:87], v[116:119], v[32:35]
	v_mfma_f32_16x16x32_bf16 v[60:63], v[80:83], v[96:99], v[60:63]
	v_mfma_f32_16x16x32_bf16 v[56:59], v[88:91], v[96:99], v[56:59]
	v_mfma_f32_16x16x32_bf16 v[52:55], v[80:83], v[104:107], v[52:55]
	v_mfma_f32_16x16x32_bf16 v[48:51], v[88:91], v[104:107], v[48:51]
	v_mfma_f32_16x16x32_bf16 v[44:47], v[80:83], v[112:115], v[44:47]
	v_mfma_f32_16x16x32_bf16 v[40:43], v[88:91], v[112:115], v[40:43]
	v_mfma_f32_16x16x32_bf16 v[36:39], v[80:83], v[120:123], v[36:39]
	v_mfma_f32_16x16x32_bf16 v[32:35], v[88:91], v[120:123], v[32:35]
	s_setprio 0
	s_barrier
	s_add_i32 s46, s53, s51
	s_add_i32 m0, s46, 0xffffff80
	ds_read_b128 v[92:95], v75 offset:49152
	ds_read_b128 v[96:99], v75 offset:50176
	ds_read_b128 v[100:103], v75 offset:51200
	ds_read_b128 v[104:107], v75 offset:52224
	ds_read_b128 v[108:111], v75 offset:53248
	ds_read_b128 v[112:115], v75 offset:54272
	ds_read_b128 v[116:119], v75 offset:55296
	ds_read_b128 v[120:123], v75 offset:56320
	global_load_lds_dwordx4 v164, s[54:55] offset:128
	s_add_i32 m0, s46, 0x1f80
	s_nop 0
	global_load_lds_dwordx4 v68, s[54:55] offset:128
	s_add_i32 m0, s89, 0xffffff80
	s_nop 0
	global_load_lds_dwordx4 v64, s[98:99] offset:128
	s_add_i32 m0, s90, 0xffffff80
	s_nop 0
	global_load_lds_dwordx4 v66, s[98:99] offset:128
	s_waitcnt vmcnt(6)
	s_waitcnt lgkmcnt(0)
	s_barrier
	s_setprio 1
	s_waitcnt lgkmcnt(0)
	v_mfma_f32_16x16x32_bf16 v[28:31], v[76:79], v[92:95], v[28:31]
	v_mfma_f32_16x16x32_bf16 v[24:27], v[84:87], v[92:95], v[24:27]
	v_mfma_f32_16x16x32_bf16 v[20:23], v[76:79], v[100:103], v[20:23]
	v_mfma_f32_16x16x32_bf16 v[16:19], v[84:87], v[100:103], v[16:19]
	v_mfma_f32_16x16x32_bf16 v[12:15], v[76:79], v[108:111], v[12:15]
	v_mfma_f32_16x16x32_bf16 v[8:11], v[84:87], v[108:111], v[8:11]
	v_mfma_f32_16x16x32_bf16 v[4:7], v[76:79], v[116:119], v[4:7]
	v_mfma_f32_16x16x32_bf16 v[0:3], v[84:87], v[116:119], v[0:3]
	v_mfma_f32_16x16x32_bf16 v[28:31], v[80:83], v[96:99], v[28:31]
	v_mfma_f32_16x16x32_bf16 v[24:27], v[88:91], v[96:99], v[24:27]
	v_mfma_f32_16x16x32_bf16 v[20:23], v[80:83], v[104:107], v[20:23]
	v_mfma_f32_16x16x32_bf16 v[16:19], v[88:91], v[104:107], v[16:19]
	v_mfma_f32_16x16x32_bf16 v[12:15], v[80:83], v[112:115], v[12:15]
	v_mfma_f32_16x16x32_bf16 v[8:11], v[88:91], v[112:115], v[8:11]
	v_mfma_f32_16x16x32_bf16 v[4:7], v[80:83], v[120:123], v[4:7]
	v_mfma_f32_16x16x32_bf16 v[0:3], v[88:91], v[120:123], v[0:3]
	s_setprio 0
	s_barrier
	s_add_u32 vcc_lo, vcc_lo, 0x100
	s_addc_u32 vcc_hi, vcc_hi, 0
	s_add_u32 s42, s42, 0x100
	s_addc_u32 s43, s43, 0
	s_cmp_ge_i32 s52, s33
	s_mov_b32 s46, s52
	s_cbranch_scc0 .LBB0_181
	s_and_b64 vcc, exec, s[10:11]
	s_cbranch_vccz .LBB0_184

.LBB0_239:
	s_add_i32 s52, s42, 2
	s_add_u32 s43, s38, 0xffff0080
	s_addc_u32 s46, s39, -1
	s_add_i32 s53, 0, 0x10000
	s_cmp_eq_u32 s19, s42
	s_cselect_b32 s47, s11, s46
	s_cselect_b32 s46, s10, s43
	s_cselect_b32 s43, s15, s76
	s_cselect_b32 s42, s14, s33
	s_mov_b64 s[98:99], s[46:47]
	s_add_i32 s60, 0, 0x14000
	v_add_u32_e32 v152, s53, v138
	v_add_u32_e32 v170, s60, v138
	ds_read_b128 v[140:143], v152
	ds_read_b128 v[144:147], v152 offset:1024
	ds_read_b128 v[148:151], v152 offset:2048
	ds_read_b128 v[152:155], v152 offset:3072
	ds_read_b128 v[156:159], v170
	ds_read_b128 v[160:163], v170 offset:1024
	ds_read_b128 v[166:169], v170 offset:2048
	ds_read_b128 v[170:173], v170 offset:3072
	s_add_i32 m0, s56, 0xc000
	ds_read_b128 v[174:177], v139
	ds_read_b128 v[178:181], v139 offset:1024
	ds_read_b128 v[182:185], v139 offset:2048
	ds_read_b128 v[186:189], v139 offset:3072
	ds_read_b128 v[212:215], v139 offset:4096
	ds_read_b128 v[216:219], v139 offset:5120
	ds_read_b128 v[220:223], v139 offset:6144
	ds_read_b128 v[224:227], v139 offset:7168
	global_load_lds_dwordx4 v136, s[38:39]
	s_add_i32 m0, s56, 0xe000
	s_nop 0
	global_load_lds_dwordx4 v134, s[38:39]
	s_waitcnt vmcnt(8)
	s_waitcnt lgkmcnt(0)
	s_barrier
	s_setprio 1
	s_waitcnt lgkmcnt(0)
	v_mfma_f32_16x16x32_bf16 v[124:127], v[140:143], v[174:177], v[124:127]
	v_mfma_f32_16x16x32_bf16 v[120:123], v[148:151], v[174:177], v[120:123]
	v_mfma_f32_16x16x32_bf16 v[108:111], v[140:143], v[182:185], v[108:111]
	v_mfma_f32_16x16x32_bf16 v[104:107], v[148:151], v[182:185], v[104:107]
	v_mfma_f32_16x16x32_bf16 v[92:95], v[140:143], v[212:215], v[92:95]
	v_mfma_f32_16x16x32_bf16 v[88:91], v[148:151], v[212:215], v[88:91]
	v_mfma_f32_16x16x32_bf16 v[76:79], v[140:143], v[220:223], v[76:79]
	v_mfma_f32_16x16x32_bf16 v[72:75], v[148:151], v[220:223], v[72:75]
	v_mfma_f32_16x16x32_bf16 v[124:127], v[144:147], v[178:181], v[124:127]
	v_mfma_f32_16x16x32_bf16 v[120:123], v[152:155], v[178:181], v[120:123]
	v_mfma_f32_16x16x32_bf16 v[108:111], v[144:147], v[186:189], v[108:111]
	v_mfma_f32_16x16x32_bf16 v[104:107], v[152:155], v[186:189], v[104:107]
	v_mfma_f32_16x16x32_bf16 v[92:95], v[144:147], v[216:219], v[92:95]
	v_mfma_f32_16x16x32_bf16 v[88:91], v[152:155], v[216:219], v[88:91]
	v_mfma_f32_16x16x32_bf16 v[76:79], v[144:147], v[224:227], v[76:79]
	v_mfma_f32_16x16x32_bf16 v[72:75], v[152:155], v[224:227], v[72:75]
	s_setprio 0
	s_setprio 1
	v_mfma_f32_16x16x32_bf16 v[116:119], v[156:159], v[174:177], v[116:119]
	v_mfma_f32_16x16x32_bf16 v[112:115], v[166:169], v[174:177], v[112:115]
	v_mfma_f32_16x16x32_bf16 v[100:103], v[156:159], v[182:185], v[100:103]
	v_mfma_f32_16x16x32_bf16 v[96:99], v[166:169], v[182:185], v[96:99]
	v_mfma_f32_16x16x32_bf16 v[84:87], v[156:159], v[212:215], v[84:87]
	v_mfma_f32_16x16x32_bf16 v[80:83], v[166:169], v[212:215], v[80:83]
	v_mfma_f32_16x16x32_bf16 v[68:71], v[156:159], v[220:223], v[68:71]
	v_mfma_f32_16x16x32_bf16 v[64:67], v[166:169], v[220:223], v[64:67]
	v_mfma_f32_16x16x32_bf16 v[116:119], v[160:163], v[178:181], v[116:119]
	v_mfma_f32_16x16x32_bf16 v[112:115], v[170:173], v[178:181], v[112:115]
	v_mfma_f32_16x16x32_bf16 v[100:103], v[160:163], v[186:189], v[100:103]
	v_mfma_f32_16x16x32_bf16 v[96:99], v[170:173], v[186:189], v[96:99]
	v_mfma_f32_16x16x32_bf16 v[84:87], v[160:163], v[216:219], v[84:87]
	v_mfma_f32_16x16x32_bf16 v[80:83], v[170:173], v[216:219], v[80:83]
	v_mfma_f32_16x16x32_bf16 v[68:71], v[160:163], v[224:227], v[68:71]
	v_mfma_f32_16x16x32_bf16 v[64:67], v[170:173], v[224:227], v[64:67]
	s_setprio 0
	s_barrier
	s_add_i32 s53, s53, s51
	s_mov_b32 m0, s53
	ds_read_b128 v[174:177], v139 offset:16384
	ds_read_b128 v[178:181], v139 offset:17408
	ds_read_b128 v[182:185], v139 offset:18432
	ds_read_b128 v[186:189], v139 offset:19456
	ds_read_b128 v[212:215], v139 offset:20480
	ds_read_b128 v[216:219], v139 offset:21504
	ds_read_b128 v[220:223], v139 offset:22528
	ds_read_b128 v[224:227], v139 offset:23552
	global_load_lds_dwordx4 v164, s[42:43]
	s_add_i32 m0, s53, 0x2000
	s_add_u32 s54, s42, 0x40000
	s_addc_u32 s55, s43, 0
	s_add_i32 s53, s60, s51
	global_load_lds_dwordx4 v128, s[42:43]
	s_mov_b32 m0, s53
	s_nop 0
	global_load_lds_dwordx4 v164, s[54:55]
	s_add_i32 m0, s53, 0x2000
	s_nop 0
	global_load_lds_dwordx4 v128, s[54:55]
	s_mov_b32 m0, s56
	s_nop 0
	global_load_lds_dwordx4 v132, s[98:99]
	s_mov_b32 m0, s57
	s_nop 0
	global_load_lds_dwordx4 v130, s[98:99]
	s_waitcnt vmcnt(8)
	s_waitcnt lgkmcnt(0)
	s_barrier
	s_setprio 1
	s_waitcnt lgkmcnt(0)
	v_mfma_f32_16x16x32_bf16 v[60:63], v[140:143], v[174:177], v[60:63]
	v_mfma_f32_16x16x32_bf16 v[56:59], v[148:151], v[174:177], v[56:59]
	v_mfma_f32_16x16x32_bf16 v[44:47], v[140:143], v[182:185], v[44:47]
	v_mfma_f32_16x16x32_bf16 v[40:43], v[148:151], v[182:185], v[40:43]
	v_mfma_f32_16x16x32_bf16 v[28:31], v[140:143], v[212:215], v[28:31]
	v_mfma_f32_16x16x32_bf16 v[24:27], v[148:151], v[212:215], v[24:27]
	v_mfma_f32_16x16x32_bf16 v[12:15], v[140:143], v[220:223], v[12:15]
	v_mfma_f32_16x16x32_bf16 v[8:11], v[148:151], v[220:223], v[8:11]
	v_mfma_f32_16x16x32_bf16 v[60:63], v[144:147], v[178:181], v[60:63]
	v_mfma_f32_16x16x32_bf16 v[56:59], v[152:155], v[178:181], v[56:59]
	v_mfma_f32_16x16x32_bf16 v[44:47], v[144:147], v[186:189], v[44:47]
	v_mfma_f32_16x16x32_bf16 v[40:43], v[152:155], v[186:189], v[40:43]
	v_mfma_f32_16x16x32_bf16 v[28:31], v[144:147], v[216:219], v[28:31]
	v_mfma_f32_16x16x32_bf16 v[24:27], v[152:155], v[216:219], v[24:27]
	v_mfma_f32_16x16x32_bf16 v[12:15], v[144:147], v[224:227], v[12:15]
	v_mfma_f32_16x16x32_bf16 v[8:11], v[152:155], v[224:227], v[8:11]
	s_setprio 0
	s_setprio 1
	v_mfma_f32_16x16x32_bf16 v[52:55], v[156:159], v[174:177], v[52:55]
	v_mfma_f32_16x16x32_bf16 v[48:51], v[166:169], v[174:177], v[48:51]
	v_mfma_f32_16x16x32_bf16 v[36:39], v[156:159], v[182:185], v[36:39]
	v_mfma_f32_16x16x32_bf16 v[32:35], v[166:169], v[182:185], v[32:35]
	v_mfma_f32_16x16x32_bf16 v[20:23], v[156:159], v[212:215], v[20:23]
	v_mfma_f32_16x16x32_bf16 v[16:19], v[166:169], v[212:215], v[16:19]
	v_mfma_f32_16x16x32_bf16 v[4:7], v[156:159], v[220:223], v[4:7]
	v_mfma_f32_16x16x32_bf16 v[0:3], v[166:169], v[220:223], v[0:3]
	v_mfma_f32_16x16x32_bf16 v[52:55], v[160:163], v[178:181], v[52:55]
	v_mfma_f32_16x16x32_bf16 v[48:51], v[170:173], v[178:181], v[48:51]
	v_mfma_f32_16x16x32_bf16 v[36:39], v[160:163], v[186:189], v[36:39]
	v_mfma_f32_16x16x32_bf16 v[32:35], v[170:173], v[186:189], v[32:35]
	v_mfma_f32_16x16x32_bf16 v[20:23], v[160:163], v[216:219], v[20:23]
	v_mfma_f32_16x16x32_bf16 v[16:19], v[170:173], v[216:219], v[16:19]
	v_mfma_f32_16x16x32_bf16 v[4:7], v[160:163], v[224:227], v[4:7]
	v_mfma_f32_16x16x32_bf16 v[0:3], v[170:173], v[224:227], v[0:3]
	s_setprio 0
	s_barrier
	s_add_i32 s53, 0, 0x18000
	s_add_i32 s54, 0, 0x1c000
	v_add_u32_e32 v152, s53, v138
	v_add_u32_e32 v170, s54, v138
	ds_read_b128 v[140:143], v152
	ds_read_b128 v[144:147], v152 offset:1024
	ds_read_b128 v[148:151], v152 offset:2048
	ds_read_b128 v[152:155], v152 offset:3072
	ds_read_b128 v[156:159], v170
	ds_read_b128 v[160:163], v170 offset:1024
	ds_read_b128 v[166:169], v170 offset:2048
	ds_read_b128 v[170:173], v170 offset:3072
	s_add_u32 s46, s46, 0x10000
	s_addc_u32 s47, s47, 0
	s_mov_b32 m0, s58
	s_nop 0
	ds_read_b128 v[174:177], v139 offset:32768
	ds_read_b128 v[178:181], v139 offset:33792
	ds_read_b128 v[182:185], v139 offset:34816
	ds_read_b128 v[186:189], v139 offset:35840
	ds_read_b128 v[212:215], v139 offset:36864
	ds_read_b128 v[216:219], v139 offset:37888
	ds_read_b128 v[220:223], v139 offset:38912
	ds_read_b128 v[224:227], v139 offset:39936
	global_load_lds_dwordx4 v132, s[46:47]
	s_mov_b32 m0, s59
	s_nop 0
	global_load_lds_dwordx4 v130, s[46:47]
	s_waitcnt vmcnt(8)
	s_waitcnt lgkmcnt(0)
	s_barrier
	s_setprio 1
	s_waitcnt lgkmcnt(0)
	v_mfma_f32_16x16x32_bf16 v[124:127], v[140:143], v[174:177], v[124:127]
	v_mfma_f32_16x16x32_bf16 v[120:123], v[148:151], v[174:177], v[120:123]
	v_mfma_f32_16x16x32_bf16 v[108:111], v[140:143], v[182:185], v[108:111]
	v_mfma_f32_16x16x32_bf16 v[104:107], v[148:151], v[182:185], v[104:107]
	v_mfma_f32_16x16x32_bf16 v[92:95], v[140:143], v[212:215], v[92:95]
	v_mfma_f32_16x16x32_bf16 v[88:91], v[148:151], v[212:215], v[88:91]
	v_mfma_f32_16x16x32_bf16 v[76:79], v[140:143], v[220:223], v[76:79]
	v_mfma_f32_16x16x32_bf16 v[72:75], v[148:151], v[220:223], v[72:75]
	v_mfma_f32_16x16x32_bf16 v[124:127], v[144:147], v[178:181], v[124:127]
	v_mfma_f32_16x16x32_bf16 v[120:123], v[152:155], v[178:181], v[120:123]
	v_mfma_f32_16x16x32_bf16 v[108:111], v[144:147], v[186:189], v[108:111]
	v_mfma_f32_16x16x32_bf16 v[104:107], v[152:155], v[186:189], v[104:107]
	v_mfma_f32_16x16x32_bf16 v[92:95], v[144:147], v[216:219], v[92:95]
	v_mfma_f32_16x16x32_bf16 v[88:91], v[152:155], v[216:219], v[88:91]
	v_mfma_f32_16x16x32_bf16 v[76:79], v[144:147], v[224:227], v[76:79]
	v_mfma_f32_16x16x32_bf16 v[72:75], v[152:155], v[224:227], v[72:75]
	s_setprio 0
	s_setprio 1
	v_mfma_f32_16x16x32_bf16 v[116:119], v[156:159], v[174:177], v[116:119]
	v_mfma_f32_16x16x32_bf16 v[112:115], v[166:169], v[174:177], v[112:115]
	v_mfma_f32_16x16x32_bf16 v[100:103], v[156:159], v[182:185], v[100:103]
	v_mfma_f32_16x16x32_bf16 v[96:99], v[166:169], v[182:185], v[96:99]
	v_mfma_f32_16x16x32_bf16 v[84:87], v[156:159], v[212:215], v[84:87]
	v_mfma_f32_16x16x32_bf16 v[80:83], v[166:169], v[212:215], v[80:83]
	v_mfma_f32_16x16x32_bf16 v[68:71], v[156:159], v[220:223], v[68:71]
	v_mfma_f32_16x16x32_bf16 v[64:67], v[166:169], v[220:223], v[64:67]
	v_mfma_f32_16x16x32_bf16 v[116:119], v[160:163], v[178:181], v[116:119]
	v_mfma_f32_16x16x32_bf16 v[112:115], v[170:173], v[178:181], v[112:115]
	v_mfma_f32_16x16x32_bf16 v[100:103], v[160:163], v[186:189], v[100:103]
	v_mfma_f32_16x16x32_bf16 v[96:99], v[170:173], v[186:189], v[96:99]
	v_mfma_f32_16x16x32_bf16 v[84:87], v[160:163], v[216:219], v[84:87]
	v_mfma_f32_16x16x32_bf16 v[80:83], v[170:173], v[216:219], v[80:83]
	v_mfma_f32_16x16x32_bf16 v[68:71], v[160:163], v[224:227], v[68:71]
	v_mfma_f32_16x16x32_bf16 v[64:67], v[170:173], v[224:227], v[64:67]
	s_setprio 0
	s_barrier
	s_add_i32 s46, s53, s51
	s_add_i32 m0, s46, 0xffffff80
	ds_read_b128 v[174:177], v139 offset:49152
	ds_read_b128 v[178:181], v139 offset:50176
	ds_read_b128 v[182:185], v139 offset:51200
	ds_read_b128 v[186:189], v139 offset:52224
	ds_read_b128 v[212:215], v139 offset:53248
	ds_read_b128 v[216:219], v139 offset:54272
	ds_read_b128 v[220:223], v139 offset:55296
	ds_read_b128 v[224:227], v139 offset:56320
	global_load_lds_dwordx4 v164, s[42:43] offset:128
	s_add_i32 m0, s46, 0x1f80
	s_nop 0
	s_add_i32 s46, s54, s51
	global_load_lds_dwordx4 v128, s[42:43] offset:128
	s_add_u32 s42, s42, 0x40080
	s_addc_u32 s43, s43, 0
	s_mov_b32 m0, s46
	s_nop 0
	global_load_lds_dwordx4 v164, s[42:43]
	s_add_i32 m0, s46, 0x2000
	s_nop 0
	global_load_lds_dwordx4 v128, s[42:43]
	s_add_i32 m0, s71, 0xffffff80
	s_nop 0
	global_load_lds_dwordx4 v132, s[98:99] offset:128
	s_add_i32 m0, s72, 0xffffff80
	s_nop 0
	global_load_lds_dwordx4 v130, s[98:99] offset:128
	s_waitcnt vmcnt(8)
	s_waitcnt lgkmcnt(0)
	s_barrier
	s_setprio 1
	s_waitcnt lgkmcnt(0)
	v_mfma_f32_16x16x32_bf16 v[60:63], v[140:143], v[174:177], v[60:63]
	v_mfma_f32_16x16x32_bf16 v[56:59], v[148:151], v[174:177], v[56:59]
	v_mfma_f32_16x16x32_bf16 v[44:47], v[140:143], v[182:185], v[44:47]
	v_mfma_f32_16x16x32_bf16 v[40:43], v[148:151], v[182:185], v[40:43]
	v_mfma_f32_16x16x32_bf16 v[28:31], v[140:143], v[212:215], v[28:31]
	v_mfma_f32_16x16x32_bf16 v[24:27], v[148:151], v[212:215], v[24:27]
	v_mfma_f32_16x16x32_bf16 v[12:15], v[140:143], v[220:223], v[12:15]
	v_mfma_f32_16x16x32_bf16 v[8:11], v[148:151], v[220:223], v[8:11]
	v_mfma_f32_16x16x32_bf16 v[60:63], v[144:147], v[178:181], v[60:63]
	v_mfma_f32_16x16x32_bf16 v[56:59], v[152:155], v[178:181], v[56:59]
	v_mfma_f32_16x16x32_bf16 v[44:47], v[144:147], v[186:189], v[44:47]
	v_mfma_f32_16x16x32_bf16 v[40:43], v[152:155], v[186:189], v[40:43]
	v_mfma_f32_16x16x32_bf16 v[28:31], v[144:147], v[216:219], v[28:31]
	v_mfma_f32_16x16x32_bf16 v[24:27], v[152:155], v[216:219], v[24:27]
	v_mfma_f32_16x16x32_bf16 v[12:15], v[144:147], v[224:227], v[12:15]
	v_mfma_f32_16x16x32_bf16 v[8:11], v[152:155], v[224:227], v[8:11]
	s_setprio 0
	s_setprio 1
	v_mfma_f32_16x16x32_bf16 v[52:55], v[156:159], v[174:177], v[52:55]
	v_mfma_f32_16x16x32_bf16 v[48:51], v[166:169], v[174:177], v[48:51]
	v_mfma_f32_16x16x32_bf16 v[36:39], v[156:159], v[182:185], v[36:39]
	v_mfma_f32_16x16x32_bf16 v[32:35], v[166:169], v[182:185], v[32:35]
	v_mfma_f32_16x16x32_bf16 v[20:23], v[156:159], v[212:215], v[20:23]
	v_mfma_f32_16x16x32_bf16 v[16:19], v[166:169], v[212:215], v[16:19]
	v_mfma_f32_16x16x32_bf16 v[4:7], v[156:159], v[220:223], v[4:7]
	v_mfma_f32_16x16x32_bf16 v[0:3], v[166:169], v[220:223], v[0:3]
	v_mfma_f32_16x16x32_bf16 v[52:55], v[160:163], v[178:181], v[52:55]
	v_mfma_f32_16x16x32_bf16 v[48:51], v[170:173], v[178:181], v[48:51]
	v_mfma_f32_16x16x32_bf16 v[36:39], v[160:163], v[186:189], v[36:39]
	v_mfma_f32_16x16x32_bf16 v[32:35], v[170:173], v[186:189], v[32:35]
	v_mfma_f32_16x16x32_bf16 v[20:23], v[160:163], v[216:219], v[20:23]
	v_mfma_f32_16x16x32_bf16 v[16:19], v[170:173], v[216:219], v[16:19]
	v_mfma_f32_16x16x32_bf16 v[4:7], v[160:163], v[224:227], v[4:7]
	v_mfma_f32_16x16x32_bf16 v[0:3], v[170:173], v[224:227], v[0:3]
	s_setprio 0
	s_barrier
	s_add_u32 s33, s33, 0x100
	s_addc_u32 s76, s76, 0
	s_add_u32 s38, s38, 0x100
	s_addc_u32 s39, s39, 0
	s_cmp_ge_i32 s52, s9
	s_mov_b32 s42, s52
	s_cbranch_scc0 .LBB0_239
	v_readlane_b32 s38, v239, 10
	v_readlane_b32 s39, v239, 11
	s_mov_b32 s60, s38
	s_and_b64 vcc, exec, s[6:7]
	s_cbranch_vccz .LBB0_242

.LBB0_284:
	s_add_i32 s54, s38, 2
	s_add_u32 s34, s18, 0x100
	s_addc_u32 s35, s19, 0
	s_add_i32 s55, 0, 0x10000
	v_add_u32_e32 v84, s55, v82
	ds_read_b128 v[70:73], v84
	ds_read_b128 v[74:77], v84 offset:1024
	ds_read_b128 v[78:81], v84 offset:2048
	ds_read_b128 v[84:87], v84 offset:3072
	s_cmp_eq_u32 vcc_hi, s38
	s_cselect_b32 s38, s12, s34
	s_cselect_b32 s39, s13, s35
	s_cselect_b32 s61, s15, s53
	s_cselect_b32 s60, s14, s52
	s_add_i32 m0, s50, 0xc000
	ds_read_b128 v[88:91], v83
	ds_read_b128 v[92:95], v83 offset:1024
	ds_read_b128 v[96:99], v83 offset:2048
	ds_read_b128 v[100:103], v83 offset:3072
	ds_read_b128 v[104:107], v83 offset:4096
	ds_read_b128 v[108:111], v83 offset:5120
	ds_read_b128 v[112:115], v83 offset:6144
	ds_read_b128 v[116:119], v83 offset:7168
	global_load_lds_dwordx4 v68, s[18:19]
	s_add_i32 m0, s50, 0xe000
	s_nop 0
	global_load_lds_dwordx4 v66, s[18:19]
	s_waitcnt vmcnt(6)
	s_waitcnt lgkmcnt(0)
	s_barrier
	s_setprio 1
	s_waitcnt lgkmcnt(0)
	v_mfma_f32_16x16x32_bf16 v[60:63], v[70:73], v[88:91], v[60:63]
	v_mfma_f32_16x16x32_bf16 v[56:59], v[78:81], v[88:91], v[56:59]
	v_mfma_f32_16x16x32_bf16 v[52:55], v[70:73], v[96:99], v[52:55]
	v_mfma_f32_16x16x32_bf16 v[48:51], v[78:81], v[96:99], v[48:51]
	v_mfma_f32_16x16x32_bf16 v[44:47], v[70:73], v[104:107], v[44:47]
	v_mfma_f32_16x16x32_bf16 v[40:43], v[78:81], v[104:107], v[40:43]
	v_mfma_f32_16x16x32_bf16 v[36:39], v[70:73], v[112:115], v[36:39]
	v_mfma_f32_16x16x32_bf16 v[32:35], v[78:81], v[112:115], v[32:35]
	v_mfma_f32_16x16x32_bf16 v[60:63], v[74:77], v[92:95], v[60:63]
	v_mfma_f32_16x16x32_bf16 v[56:59], v[84:87], v[92:95], v[56:59]
	v_mfma_f32_16x16x32_bf16 v[52:55], v[74:77], v[100:103], v[52:55]
	v_mfma_f32_16x16x32_bf16 v[48:51], v[84:87], v[100:103], v[48:51]
	v_mfma_f32_16x16x32_bf16 v[44:47], v[74:77], v[108:111], v[44:47]
	v_mfma_f32_16x16x32_bf16 v[40:43], v[84:87], v[108:111], v[40:43]
	v_mfma_f32_16x16x32_bf16 v[36:39], v[74:77], v[116:119], v[36:39]
	v_mfma_f32_16x16x32_bf16 v[32:35], v[84:87], v[116:119], v[32:35]
	s_setprio 0
	s_barrier
	s_add_i32 s18, s55, s47
	s_mov_b32 m0, s18
	ds_read_b128 v[88:91], v83 offset:16384
	ds_read_b128 v[92:95], v83 offset:17408
	ds_read_b128 v[96:99], v83 offset:18432
	ds_read_b128 v[100:103], v83 offset:19456
	ds_read_b128 v[104:107], v83 offset:20480
	ds_read_b128 v[108:111], v83 offset:21504
	ds_read_b128 v[112:115], v83 offset:22528
	ds_read_b128 v[116:119], v83 offset:23552
	global_load_lds_dwordx4 v164, s[60:61]
	s_add_i32 m0, s18, 0x2000
	s_nop 0
	global_load_lds_dwordx4 v64, s[60:61]
	s_mov_b32 m0, s50
	s_nop 0
	global_load_lds_dwordx4 v164, s[38:39]
	s_mov_b32 m0, s57
	s_nop 0
	global_load_lds_dwordx4 v64, s[38:39]
	s_waitcnt vmcnt(6)
	s_waitcnt lgkmcnt(0)
	s_barrier
	s_setprio 1
	s_waitcnt lgkmcnt(0)
	v_mfma_f32_16x16x32_bf16 v[28:31], v[70:73], v[88:91], v[28:31]
	v_mfma_f32_16x16x32_bf16 v[24:27], v[78:81], v[88:91], v[24:27]
	v_mfma_f32_16x16x32_bf16 v[20:23], v[70:73], v[96:99], v[20:23]
	v_mfma_f32_16x16x32_bf16 v[16:19], v[78:81], v[96:99], v[16:19]
	v_mfma_f32_16x16x32_bf16 v[12:15], v[70:73], v[104:107], v[12:15]
	v_mfma_f32_16x16x32_bf16 v[8:11], v[78:81], v[104:107], v[8:11]
	v_mfma_f32_16x16x32_bf16 v[4:7], v[70:73], v[112:115], v[4:7]
	v_mfma_f32_16x16x32_bf16 v[0:3], v[78:81], v[112:115], v[0:3]
	v_mfma_f32_16x16x32_bf16 v[28:31], v[74:77], v[92:95], v[28:31]
	v_mfma_f32_16x16x32_bf16 v[24:27], v[84:87], v[92:95], v[24:27]
	v_mfma_f32_16x16x32_bf16 v[20:23], v[74:77], v[100:103], v[20:23]
	v_mfma_f32_16x16x32_bf16 v[16:19], v[84:87], v[100:103], v[16:19]
	v_mfma_f32_16x16x32_bf16 v[12:15], v[74:77], v[108:111], v[12:15]
	v_mfma_f32_16x16x32_bf16 v[8:11], v[84:87], v[108:111], v[8:11]
	v_mfma_f32_16x16x32_bf16 v[4:7], v[74:77], v[116:119], v[4:7]
	v_mfma_f32_16x16x32_bf16 v[0:3], v[84:87], v[116:119], v[0:3]
	s_setprio 0
	s_barrier
	s_add_i32 s55, 0, 0x18000
	v_add_u32_e32 v84, s55, v82
	ds_read_b128 v[70:73], v84
	ds_read_b128 v[74:77], v84 offset:1024
	ds_read_b128 v[78:81], v84 offset:2048
	ds_read_b128 v[84:87], v84 offset:3072
	s_add_u32 s18, s38, 0xb0000
	s_addc_u32 s19, s39, 0
	s_mov_b32 m0, s58
	s_nop 0
	ds_read_b128 v[88:91], v83 offset:32768
	ds_read_b128 v[92:95], v83 offset:33792
	ds_read_b128 v[96:99], v83 offset:34816
	ds_read_b128 v[100:103], v83 offset:35840
	ds_read_b128 v[104:107], v83 offset:36864
	ds_read_b128 v[108:111], v83 offset:37888
	ds_read_b128 v[112:115], v83 offset:38912
	ds_read_b128 v[116:119], v83 offset:39936
	global_load_lds_dwordx4 v164, s[18:19]
	s_mov_b32 m0, s59
	s_nop 0
	global_load_lds_dwordx4 v64, s[18:19]
	s_waitcnt vmcnt(6)
	s_waitcnt lgkmcnt(0)
	s_barrier
	s_setprio 1
	s_waitcnt lgkmcnt(0)
	v_mfma_f32_16x16x32_bf16 v[60:63], v[70:73], v[88:91], v[60:63]
	v_mfma_f32_16x16x32_bf16 v[56:59], v[78:81], v[88:91], v[56:59]
	v_mfma_f32_16x16x32_bf16 v[52:55], v[70:73], v[96:99], v[52:55]
	v_mfma_f32_16x16x32_bf16 v[48:51], v[78:81], v[96:99], v[48:51]
	v_mfma_f32_16x16x32_bf16 v[44:47], v[70:73], v[104:107], v[44:47]
	v_mfma_f32_16x16x32_bf16 v[40:43], v[78:81], v[104:107], v[40:43]
	v_mfma_f32_16x16x32_bf16 v[36:39], v[70:73], v[112:115], v[36:39]
	v_mfma_f32_16x16x32_bf16 v[32:35], v[78:81], v[112:115], v[32:35]
	v_mfma_f32_16x16x32_bf16 v[60:63], v[74:77], v[92:95], v[60:63]
	v_mfma_f32_16x16x32_bf16 v[56:59], v[84:87], v[92:95], v[56:59]
	v_mfma_f32_16x16x32_bf16 v[52:55], v[74:77], v[100:103], v[52:55]
	v_mfma_f32_16x16x32_bf16 v[48:51], v[84:87], v[100:103], v[48:51]
	v_mfma_f32_16x16x32_bf16 v[44:47], v[74:77], v[108:111], v[44:47]
	v_mfma_f32_16x16x32_bf16 v[40:43], v[84:87], v[108:111], v[40:43]
	v_mfma_f32_16x16x32_bf16 v[36:39], v[74:77], v[116:119], v[36:39]
	v_mfma_f32_16x16x32_bf16 v[32:35], v[84:87], v[116:119], v[32:35]
	s_setprio 0
	s_barrier
	s_add_i32 s18, s55, s47
	s_add_i32 m0, s18, 0xffffff80
	ds_read_b128 v[88:91], v83 offset:49152
	ds_read_b128 v[92:95], v83 offset:50176
	ds_read_b128 v[96:99], v83 offset:51200
	ds_read_b128 v[100:103], v83 offset:52224
	ds_read_b128 v[104:107], v83 offset:53248
	ds_read_b128 v[108:111], v83 offset:54272
	ds_read_b128 v[112:115], v83 offset:55296
	ds_read_b128 v[116:119], v83 offset:56320
	global_load_lds_dwordx4 v164, s[60:61] offset:128
	s_add_i32 m0, s18, 0x1f80
	s_nop 0
	global_load_lds_dwordx4 v64, s[60:61] offset:128
	s_add_i32 m0, s72, 0xffffff80
	s_nop 0
	global_load_lds_dwordx4 v164, s[38:39] offset:128
	s_add_i32 m0, s73, 0xffffff80
	s_nop 0
	global_load_lds_dwordx4 v64, s[38:39] offset:128
	s_waitcnt vmcnt(6)
	s_waitcnt lgkmcnt(0)
	s_barrier
	s_setprio 1
	s_waitcnt lgkmcnt(0)
	v_mfma_f32_16x16x32_bf16 v[28:31], v[70:73], v[88:91], v[28:31]
	v_mfma_f32_16x16x32_bf16 v[24:27], v[78:81], v[88:91], v[24:27]
	v_mfma_f32_16x16x32_bf16 v[20:23], v[70:73], v[96:99], v[20:23]
	v_mfma_f32_16x16x32_bf16 v[16:19], v[78:81], v[96:99], v[16:19]
	v_mfma_f32_16x16x32_bf16 v[12:15], v[70:73], v[104:107], v[12:15]
	v_mfma_f32_16x16x32_bf16 v[8:11], v[78:81], v[104:107], v[8:11]
	v_mfma_f32_16x16x32_bf16 v[4:7], v[70:73], v[112:115], v[4:7]
	v_mfma_f32_16x16x32_bf16 v[0:3], v[78:81], v[112:115], v[0:3]
	v_mfma_f32_16x16x32_bf16 v[28:31], v[74:77], v[92:95], v[28:31]
	v_mfma_f32_16x16x32_bf16 v[24:27], v[84:87], v[92:95], v[24:27]
	v_mfma_f32_16x16x32_bf16 v[20:23], v[74:77], v[100:103], v[20:23]
	v_mfma_f32_16x16x32_bf16 v[16:19], v[84:87], v[100:103], v[16:19]
	v_mfma_f32_16x16x32_bf16 v[12:15], v[74:77], v[108:111], v[12:15]
	v_mfma_f32_16x16x32_bf16 v[8:11], v[84:87], v[108:111], v[8:11]
	v_mfma_f32_16x16x32_bf16 v[4:7], v[74:77], v[116:119], v[4:7]
	v_mfma_f32_16x16x32_bf16 v[0:3], v[84:87], v[116:119], v[0:3]
	s_setprio 0
	s_barrier
	s_add_u32 s52, s52, 0x100
	s_addc_u32 s53, s53, 0
	s_cmp_ge_i32 s54, vcc_lo
	s_mov_b64 s[18:19], s[34:35]
	s_mov_b32 s38, s54
	s_cbranch_scc0 .LBB0_284
	v_pk_add_f32 v[78:79], v[62:63], 0 op_sel_hi:[1,0]
	v_pk_add_f32 v[80:81], v[60:61], 0 op_sel_hi:[1,0]
	v_pk_add_f32 v[74:75], v[58:59], 0 op_sel_hi:[1,0]
	v_pk_add_f32 v[76:77], v[56:57], 0 op_sel_hi:[1,0]
	v_pk_add_f32 v[62:63], v[54:55], 0 op_sel_hi:[1,0]
	v_pk_add_f32 v[70:71], v[52:53], 0 op_sel_hi:[1,0]
	v_pk_add_f32 v[56:57], v[50:51], 0 op_sel_hi:[1,0]
	v_pk_add_f32 v[58:59], v[48:49], 0 op_sel_hi:[1,0]
	v_pk_add_f32 v[52:53], v[46:47], 0 op_sel_hi:[1,0]
	v_pk_add_f32 v[54:55], v[44:45], 0 op_sel_hi:[1,0]
	v_pk_add_f32 v[48:49], v[42:43], 0 op_sel_hi:[1,0]
	v_pk_add_f32 v[50:51], v[40:41], 0 op_sel_hi:[1,0]
	v_pk_add_f32 v[44:45], v[38:39], 0 op_sel_hi:[1,0]
	v_pk_add_f32 v[46:47], v[36:37], 0 op_sel_hi:[1,0]
	v_pk_add_f32 v[40:41], v[34:35], 0 op_sel_hi:[1,0]
	v_pk_add_f32 v[42:43], v[32:33], 0 op_sel_hi:[1,0]
	v_pk_add_f32 v[36:37], v[30:31], 0 op_sel_hi:[1,0]
	v_pk_add_f32 v[38:39], v[28:29], 0 op_sel_hi:[1,0]
	v_pk_add_f32 v[32:33], v[26:27], 0 op_sel_hi:[1,0]
	v_pk_add_f32 v[34:35], v[24:25], 0 op_sel_hi:[1,0]
	v_pk_add_f32 v[28:29], v[22:23], 0 op_sel_hi:[1,0]
	v_pk_add_f32 v[30:31], v[20:21], 0 op_sel_hi:[1,0]
	v_pk_add_f32 v[24:25], v[18:19], 0 op_sel_hi:[1,0]
	v_pk_add_f32 v[26:27], v[16:17], 0 op_sel_hi:[1,0]
	v_pk_add_f32 v[20:21], v[14:15], 0 op_sel_hi:[1,0]
	v_pk_add_f32 v[22:23], v[12:13], 0 op_sel_hi:[1,0]
	v_pk_add_f32 v[16:17], v[10:11], 0 op_sel_hi:[1,0]
	v_pk_add_f32 v[18:19], v[8:9], 0 op_sel_hi:[1,0]
	v_pk_add_f32 v[12:13], v[6:7], 0 op_sel_hi:[1,0]
	v_pk_add_f32 v[14:15], v[4:5], 0 op_sel_hi:[1,0]
	v_pk_add_f32 v[10:11], v[2:3], 0 op_sel_hi:[1,0]
	v_pk_add_f32 v[8:9], v[0:1], 0 op_sel_hi:[1,0]
	v_readlane_b32 s60, v239, 10
	v_readlane_b32 s61, v239, 11
	s_and_b64 vcc, exec, s[8:9]
	s_cbranch_vccz .LBB0_287
